# v037 plus removal of the redundant mid-section setprio pairs and the repeated lgkmcnt(0) after each phase barrier in the K-loop MFMA sections
# baseline (speedup 1.0000x reference)
.LBB0_221:
	s_add_u32 s42, s38, 0xfffc0080
	s_addc_u32 s43, s39, -1
	s_add_i32 s61, 0, 0x10000
	s_cmp_eq_u32 s59, 12
	s_cselect_b32 s45, s11, s43
	s_cselect_b32 s44, s13, s42
	s_cselect_b32 s43, s55, s58
	s_cselect_b32 s42, s56, s57
	s_add_i32 s64, 0, 0x14000
	v_add_u32_e32 v156, s61, v150
	v_add_u32_e32 v172, s64, v150
	ds_read_b128 v[140:143], v156
	ds_read_b128 v[144:147], v156 offset:1024
	ds_read_b128 v[152:155], v156 offset:2048
	ds_read_b128 v[156:159], v156 offset:3072
	ds_read_b128 v[160:163], v172
	ds_read_b128 v[164:167], v172 offset:1024
	ds_read_b128 v[168:171], v172 offset:2048
	ds_read_b128 v[172:175], v172 offset:3072
	v_lshl_add_u64 v[218:219], s[38:39], 0, v[138:139]
	s_add_i32 m0, s33, 0xc000
	ds_read_b128 v[176:179], v151
	ds_read_b128 v[180:183], v151 offset:1024
	ds_read_b128 v[184:187], v151 offset:2048
	ds_read_b128 v[188:191], v151 offset:3072
	ds_read_b128 v[194:197], v151 offset:4096
	ds_read_b128 v[198:201], v151 offset:5120
	ds_read_b128 v[202:205], v151 offset:6144
	ds_read_b128 v[214:217], v151 offset:7168
	global_load_lds_dwordx4 v[218:219], off
	v_lshl_add_u64 v[218:219], s[38:39], 0, v[136:137]
	s_add_i32 m0, s33, 0xe000
	s_nop 0
	global_load_lds_dwordx4 v[218:219], off
	s_waitcnt vmcnt(8)
	s_waitcnt lgkmcnt(0)
	s_barrier
	s_setprio 1
	v_mfma_f32_16x16x32_bf16 v[124:127], v[140:143], v[176:179], v[124:127]
	v_mfma_f32_16x16x32_bf16 v[120:123], v[152:155], v[176:179], v[120:123]
	v_mfma_f32_16x16x32_bf16 v[108:111], v[140:143], v[184:187], v[108:111]
	v_mfma_f32_16x16x32_bf16 v[104:107], v[152:155], v[184:187], v[104:107]
	v_mfma_f32_16x16x32_bf16 v[92:95], v[140:143], v[194:197], v[92:95]
	v_mfma_f32_16x16x32_bf16 v[88:91], v[152:155], v[194:197], v[88:91]
	v_mfma_f32_16x16x32_bf16 v[76:79], v[140:143], v[202:205], v[76:79]
	v_mfma_f32_16x16x32_bf16 v[72:75], v[152:155], v[202:205], v[72:75]
	v_mfma_f32_16x16x32_bf16 v[124:127], v[144:147], v[180:183], v[124:127]
	v_mfma_f32_16x16x32_bf16 v[120:123], v[156:159], v[180:183], v[120:123]
	v_mfma_f32_16x16x32_bf16 v[108:111], v[144:147], v[188:191], v[108:111]
	v_mfma_f32_16x16x32_bf16 v[104:107], v[156:159], v[188:191], v[104:107]
	v_mfma_f32_16x16x32_bf16 v[92:95], v[144:147], v[198:201], v[92:95]
	v_mfma_f32_16x16x32_bf16 v[88:91], v[156:159], v[198:201], v[88:91]
	v_mfma_f32_16x16x32_bf16 v[76:79], v[144:147], v[214:217], v[76:79]
	v_mfma_f32_16x16x32_bf16 v[72:75], v[156:159], v[214:217], v[72:75]
	v_mfma_f32_16x16x32_bf16 v[116:119], v[160:163], v[176:179], v[116:119]
	v_mfma_f32_16x16x32_bf16 v[112:115], v[168:171], v[176:179], v[112:115]
	v_mfma_f32_16x16x32_bf16 v[100:103], v[160:163], v[184:187], v[100:103]
	v_mfma_f32_16x16x32_bf16 v[96:99], v[168:171], v[184:187], v[96:99]
	v_mfma_f32_16x16x32_bf16 v[84:87], v[160:163], v[194:197], v[84:87]
	v_mfma_f32_16x16x32_bf16 v[80:83], v[168:171], v[194:197], v[80:83]
	v_mfma_f32_16x16x32_bf16 v[68:71], v[160:163], v[202:205], v[68:71]
	v_mfma_f32_16x16x32_bf16 v[64:67], v[168:171], v[202:205], v[64:67]
	v_mfma_f32_16x16x32_bf16 v[116:119], v[164:167], v[180:183], v[116:119]
	v_mfma_f32_16x16x32_bf16 v[112:115], v[172:175], v[180:183], v[112:115]
	v_mfma_f32_16x16x32_bf16 v[100:103], v[164:167], v[188:191], v[100:103]
	v_mfma_f32_16x16x32_bf16 v[96:99], v[172:175], v[188:191], v[96:99]
	v_mfma_f32_16x16x32_bf16 v[84:87], v[164:167], v[198:201], v[84:87]
	v_mfma_f32_16x16x32_bf16 v[80:83], v[172:175], v[198:201], v[80:83]
	v_mfma_f32_16x16x32_bf16 v[68:71], v[164:167], v[214:217], v[68:71]
	v_mfma_f32_16x16x32_bf16 v[64:67], v[172:175], v[214:217], v[64:67]
	s_setprio 0
	s_barrier
	s_add_i32 s61, s61, s27
	v_lshl_add_u64 v[218:219], s[42:43], 0, v[132:133]
	s_mov_b32 m0, s61
	ds_read_b128 v[176:179], v151 offset:16384
	ds_read_b128 v[180:183], v151 offset:17408
	ds_read_b128 v[184:187], v151 offset:18432
	ds_read_b128 v[188:191], v151 offset:19456
	ds_read_b128 v[194:197], v151 offset:20480
	ds_read_b128 v[198:201], v151 offset:21504
	ds_read_b128 v[202:205], v151 offset:22528
	ds_read_b128 v[214:217], v151 offset:23552
	global_load_lds_dwordx4 v[218:219], off
	s_add_i32 m0, s61, 0x2000
	s_add_u32 s62, s42, 0x40000
	v_lshl_add_u64 v[220:221], s[42:43], 0, v[128:129]
	s_addc_u32 s63, s43, 0
	s_add_i32 s61, s64, s27
	global_load_lds_dwordx4 v[220:221], off
	v_lshl_add_u64 v[222:223], s[62:63], 0, v[132:133]
	s_mov_b32 m0, s61
	v_lshl_add_u64 v[224:225], s[44:45], 0, v[130:131]
	global_load_lds_dwordx4 v[222:223], off
	v_lshl_add_u64 v[222:223], s[62:63], 0, v[128:129]
	s_add_i32 m0, s61, 0x2000
	s_nop 0
	global_load_lds_dwordx4 v[222:223], off
	v_lshl_add_u64 v[222:223], s[44:45], 0, v[134:135]
	s_mov_b32 m0, s33
	s_nop 0
	global_load_lds_dwordx4 v[222:223], off
	s_mov_b32 m0, s40
	s_nop 0
	global_load_lds_dwordx4 v[224:225], off
	s_waitcnt vmcnt(8)
	s_waitcnt lgkmcnt(0)
	s_barrier
	s_setprio 1
	v_mfma_f32_16x16x32_bf16 v[60:63], v[140:143], v[176:179], v[60:63]
	v_mfma_f32_16x16x32_bf16 v[56:59], v[152:155], v[176:179], v[56:59]
	v_mfma_f32_16x16x32_bf16 v[44:47], v[140:143], v[184:187], v[44:47]
	v_mfma_f32_16x16x32_bf16 v[40:43], v[152:155], v[184:187], v[40:43]
	v_mfma_f32_16x16x32_bf16 v[28:31], v[140:143], v[194:197], v[28:31]
	v_mfma_f32_16x16x32_bf16 v[24:27], v[152:155], v[194:197], v[24:27]
	v_mfma_f32_16x16x32_bf16 v[12:15], v[140:143], v[202:205], v[12:15]
	v_mfma_f32_16x16x32_bf16 v[8:11], v[152:155], v[202:205], v[8:11]
	v_mfma_f32_16x16x32_bf16 v[60:63], v[144:147], v[180:183], v[60:63]
	v_mfma_f32_16x16x32_bf16 v[56:59], v[156:159], v[180:183], v[56:59]
	v_mfma_f32_16x16x32_bf16 v[44:47], v[144:147], v[188:191], v[44:47]
	v_mfma_f32_16x16x32_bf16 v[40:43], v[156:159], v[188:191], v[40:43]
	v_mfma_f32_16x16x32_bf16 v[28:31], v[144:147], v[198:201], v[28:31]
	v_mfma_f32_16x16x32_bf16 v[24:27], v[156:159], v[198:201], v[24:27]
	v_mfma_f32_16x16x32_bf16 v[12:15], v[144:147], v[214:217], v[12:15]
	v_mfma_f32_16x16x32_bf16 v[8:11], v[156:159], v[214:217], v[8:11]
	v_mfma_f32_16x16x32_bf16 v[52:55], v[160:163], v[176:179], v[52:55]
	v_mfma_f32_16x16x32_bf16 v[48:51], v[168:171], v[176:179], v[48:51]
	v_mfma_f32_16x16x32_bf16 v[36:39], v[160:163], v[184:187], v[36:39]
	v_mfma_f32_16x16x32_bf16 v[32:35], v[168:171], v[184:187], v[32:35]
	v_mfma_f32_16x16x32_bf16 v[20:23], v[160:163], v[194:197], v[20:23]
	v_mfma_f32_16x16x32_bf16 v[16:19], v[168:171], v[194:197], v[16:19]
	v_mfma_f32_16x16x32_bf16 v[4:7], v[160:163], v[202:205], v[4:7]
	v_mfma_f32_16x16x32_bf16 v[0:3], v[168:171], v[202:205], v[0:3]
	v_mfma_f32_16x16x32_bf16 v[52:55], v[164:167], v[180:183], v[52:55]
	v_mfma_f32_16x16x32_bf16 v[48:51], v[172:175], v[180:183], v[48:51]
	v_mfma_f32_16x16x32_bf16 v[36:39], v[164:167], v[188:191], v[36:39]
	v_mfma_f32_16x16x32_bf16 v[32:35], v[172:175], v[188:191], v[32:35]
	v_mfma_f32_16x16x32_bf16 v[20:23], v[164:167], v[198:201], v[20:23]
	v_mfma_f32_16x16x32_bf16 v[16:19], v[172:175], v[198:201], v[16:19]
	v_mfma_f32_16x16x32_bf16 v[4:7], v[164:167], v[214:217], v[4:7]
	v_mfma_f32_16x16x32_bf16 v[0:3], v[172:175], v[214:217], v[0:3]
	s_setprio 0
	s_barrier
	s_add_i32 s61, 0, 0x18000
	s_add_i32 s62, 0, 0x1c000
	v_add_u32_e32 v156, s61, v150
	v_add_u32_e32 v172, s62, v150
	ds_read_b128 v[140:143], v156
	ds_read_b128 v[144:147], v156 offset:1024
	ds_read_b128 v[152:155], v156 offset:2048
	ds_read_b128 v[156:159], v156 offset:3072
	ds_read_b128 v[160:163], v172
	ds_read_b128 v[164:167], v172 offset:1024
	ds_read_b128 v[168:171], v172 offset:2048
	ds_read_b128 v[172:175], v172 offset:3072
	s_add_u32 s44, s44, 0x40000
	s_addc_u32 s45, s45, 0
	s_mov_b32 m0, s46
	v_lshl_add_u64 v[226:227], s[44:45], 0, v[134:135]
	ds_read_b128 v[176:179], v151 offset:32768
	ds_read_b128 v[180:183], v151 offset:33792
	ds_read_b128 v[184:187], v151 offset:34816
	ds_read_b128 v[188:191], v151 offset:35840
	ds_read_b128 v[194:197], v151 offset:36864
	ds_read_b128 v[198:201], v151 offset:37888
	ds_read_b128 v[202:205], v151 offset:38912
	ds_read_b128 v[214:217], v151 offset:39936
	global_load_lds_dwordx4 v[226:227], off
	v_lshl_add_u64 v[226:227], s[44:45], 0, v[130:131]
	s_mov_b32 m0, s47
	s_nop 0
	global_load_lds_dwordx4 v[226:227], off
	s_waitcnt vmcnt(8)
	s_waitcnt lgkmcnt(0)
	s_barrier
	s_setprio 1
	v_mfma_f32_16x16x32_bf16 v[124:127], v[140:143], v[176:179], v[124:127]
	v_mfma_f32_16x16x32_bf16 v[120:123], v[152:155], v[176:179], v[120:123]
	v_mfma_f32_16x16x32_bf16 v[108:111], v[140:143], v[184:187], v[108:111]
	v_mfma_f32_16x16x32_bf16 v[104:107], v[152:155], v[184:187], v[104:107]
	v_mfma_f32_16x16x32_bf16 v[92:95], v[140:143], v[194:197], v[92:95]
	v_mfma_f32_16x16x32_bf16 v[88:91], v[152:155], v[194:197], v[88:91]
	v_mfma_f32_16x16x32_bf16 v[76:79], v[140:143], v[202:205], v[76:79]
	v_mfma_f32_16x16x32_bf16 v[72:75], v[152:155], v[202:205], v[72:75]
	v_mfma_f32_16x16x32_bf16 v[124:127], v[144:147], v[180:183], v[124:127]
	v_mfma_f32_16x16x32_bf16 v[120:123], v[156:159], v[180:183], v[120:123]
	v_mfma_f32_16x16x32_bf16 v[108:111], v[144:147], v[188:191], v[108:111]
	v_mfma_f32_16x16x32_bf16 v[104:107], v[156:159], v[188:191], v[104:107]
	v_mfma_f32_16x16x32_bf16 v[92:95], v[144:147], v[198:201], v[92:95]
	v_mfma_f32_16x16x32_bf16 v[88:91], v[156:159], v[198:201], v[88:91]
	v_mfma_f32_16x16x32_bf16 v[76:79], v[144:147], v[214:217], v[76:79]
	v_mfma_f32_16x16x32_bf16 v[72:75], v[156:159], v[214:217], v[72:75]
	v_mfma_f32_16x16x32_bf16 v[116:119], v[160:163], v[176:179], v[116:119]
	v_mfma_f32_16x16x32_bf16 v[112:115], v[168:171], v[176:179], v[112:115]
	v_mfma_f32_16x16x32_bf16 v[100:103], v[160:163], v[184:187], v[100:103]
	v_mfma_f32_16x16x32_bf16 v[96:99], v[168:171], v[184:187], v[96:99]
	v_mfma_f32_16x16x32_bf16 v[84:87], v[160:163], v[194:197], v[84:87]
	v_mfma_f32_16x16x32_bf16 v[80:83], v[168:171], v[194:197], v[80:83]
	v_mfma_f32_16x16x32_bf16 v[68:71], v[160:163], v[202:205], v[68:71]
	v_mfma_f32_16x16x32_bf16 v[64:67], v[168:171], v[202:205], v[64:67]
	v_mfma_f32_16x16x32_bf16 v[116:119], v[164:167], v[180:183], v[116:119]
	v_mfma_f32_16x16x32_bf16 v[112:115], v[172:175], v[180:183], v[112:115]
	v_mfma_f32_16x16x32_bf16 v[100:103], v[164:167], v[188:191], v[100:103]
	v_mfma_f32_16x16x32_bf16 v[96:99], v[172:175], v[188:191], v[96:99]
	v_mfma_f32_16x16x32_bf16 v[84:87], v[164:167], v[198:201], v[84:87]
	v_mfma_f32_16x16x32_bf16 v[80:83], v[172:175], v[198:201], v[80:83]
	v_mfma_f32_16x16x32_bf16 v[68:71], v[164:167], v[214:217], v[68:71]
	v_mfma_f32_16x16x32_bf16 v[64:67], v[172:175], v[214:217], v[64:67]
	s_setprio 0
	s_barrier
	s_add_i32 s44, s61, s27
	v_lshl_add_u64 v[218:219], v[218:219], 0, s[76:77]
	s_mov_b32 m0, s44
	ds_read_b128 v[176:179], v151 offset:49152
	ds_read_b128 v[180:183], v151 offset:50176
	ds_read_b128 v[184:187], v151 offset:51200
	ds_read_b128 v[188:191], v151 offset:52224
	ds_read_b128 v[194:197], v151 offset:53248
	ds_read_b128 v[198:201], v151 offset:54272
	ds_read_b128 v[202:205], v151 offset:55296
	ds_read_b128 v[214:217], v151 offset:56320
	global_load_lds_dwordx4 v[218:219], off
	s_add_i32 m0, s44, 0x2000
	s_add_u32 s42, s42, 0x40080
	v_lshl_add_u64 v[218:219], v[220:221], 0, s[76:77]
	s_addc_u32 s43, s43, 0
	s_add_i32 s44, s62, s27
	global_load_lds_dwordx4 v[218:219], off
	v_lshl_add_u64 v[218:219], s[42:43], 0, v[132:133]
	s_mov_b32 m0, s44
	s_nop 0
	global_load_lds_dwordx4 v[218:219], off
	v_lshl_add_u64 v[218:219], s[42:43], 0, v[128:129]
	s_add_i32 m0, s44, 0x2000
	s_nop 0
	global_load_lds_dwordx4 v[218:219], off
	v_lshl_add_u64 v[218:219], v[222:223], 0, s[76:77]
	s_mov_b32 m0, s52
	s_nop 0
	global_load_lds_dwordx4 v[218:219], off
	v_lshl_add_u64 v[218:219], v[224:225], 0, s[76:77]
	s_mov_b32 m0, s53
	s_nop 0
	global_load_lds_dwordx4 v[218:219], off
	s_waitcnt vmcnt(8)
	s_waitcnt lgkmcnt(0)
	s_barrier
	s_setprio 1
	v_mfma_f32_16x16x32_bf16 v[60:63], v[140:143], v[176:179], v[60:63]
	v_mfma_f32_16x16x32_bf16 v[56:59], v[152:155], v[176:179], v[56:59]
	v_mfma_f32_16x16x32_bf16 v[44:47], v[140:143], v[184:187], v[44:47]
	v_mfma_f32_16x16x32_bf16 v[40:43], v[152:155], v[184:187], v[40:43]
	v_mfma_f32_16x16x32_bf16 v[28:31], v[140:143], v[194:197], v[28:31]
	v_mfma_f32_16x16x32_bf16 v[24:27], v[152:155], v[194:197], v[24:27]
	v_mfma_f32_16x16x32_bf16 v[12:15], v[140:143], v[202:205], v[12:15]
	v_mfma_f32_16x16x32_bf16 v[8:11], v[152:155], v[202:205], v[8:11]
	v_mfma_f32_16x16x32_bf16 v[60:63], v[144:147], v[180:183], v[60:63]
	v_mfma_f32_16x16x32_bf16 v[56:59], v[156:159], v[180:183], v[56:59]
	v_mfma_f32_16x16x32_bf16 v[44:47], v[144:147], v[188:191], v[44:47]
	v_mfma_f32_16x16x32_bf16 v[40:43], v[156:159], v[188:191], v[40:43]
	v_mfma_f32_16x16x32_bf16 v[28:31], v[144:147], v[198:201], v[28:31]
	v_mfma_f32_16x16x32_bf16 v[24:27], v[156:159], v[198:201], v[24:27]
	v_mfma_f32_16x16x32_bf16 v[12:15], v[144:147], v[214:217], v[12:15]
	v_mfma_f32_16x16x32_bf16 v[8:11], v[156:159], v[214:217], v[8:11]
	v_mfma_f32_16x16x32_bf16 v[52:55], v[160:163], v[176:179], v[52:55]
	v_mfma_f32_16x16x32_bf16 v[48:51], v[168:171], v[176:179], v[48:51]
	v_mfma_f32_16x16x32_bf16 v[36:39], v[160:163], v[184:187], v[36:39]
	v_mfma_f32_16x16x32_bf16 v[32:35], v[168:171], v[184:187], v[32:35]
	v_mfma_f32_16x16x32_bf16 v[20:23], v[160:163], v[194:197], v[20:23]
	v_mfma_f32_16x16x32_bf16 v[16:19], v[168:171], v[194:197], v[16:19]
	v_mfma_f32_16x16x32_bf16 v[4:7], v[160:163], v[202:205], v[4:7]
	v_mfma_f32_16x16x32_bf16 v[0:3], v[168:171], v[202:205], v[0:3]
	v_mfma_f32_16x16x32_bf16 v[52:55], v[164:167], v[180:183], v[52:55]
	v_mfma_f32_16x16x32_bf16 v[48:51], v[172:175], v[180:183], v[48:51]
	v_mfma_f32_16x16x32_bf16 v[36:39], v[164:167], v[188:191], v[36:39]
	v_mfma_f32_16x16x32_bf16 v[32:35], v[172:175], v[188:191], v[32:35]
	s_add_i32 s59, s59, 2
	s_add_u32 s57, s57, 0x100
	s_addc_u32 s58, s58, 0
	s_add_u32 s38, s38, 0x100
	s_addc_u32 s39, s39, 0
	v_mfma_f32_16x16x32_bf16 v[20:23], v[164:167], v[198:201], v[20:23]
	v_mfma_f32_16x16x32_bf16 v[16:19], v[172:175], v[198:201], v[16:19]
	v_mfma_f32_16x16x32_bf16 v[4:7], v[164:167], v[214:217], v[4:7]
	v_mfma_f32_16x16x32_bf16 v[0:3], v[172:175], v[214:217], v[0:3]
	s_setprio 0
	s_barrier
	s_cmp_gt_u32 s59, 13
	s_cbranch_scc0 .LBB0_221
	s_and_b64 vcc, exec, s[8:9]
	s_cbranch_vccz .LBB0_224
	s_barrier

.LBB0_299:
	s_add_u32 s14, s12, 0xfffc0080
	s_addc_u32 s15, s13, -1
	s_add_i32 s40, 0, 0x10000
	s_cmp_eq_u32 s39, 12
	s_cselect_b32 s17, s9, s15
	s_cselect_b32 s16, s11, s14
	s_cselect_b32 s15, s30, s38
	s_cselect_b32 s14, s31, s33
	s_add_i32 s52, 0, 0x14000
	v_add_u32_e32 v140, s40, v178
	v_add_u32_e32 v168, s52, v178
	ds_read_b128 v[128:131], v140
	ds_read_b128 v[132:135], v140 offset:1024
	ds_read_b128 v[136:139], v140 offset:2048
	ds_read_b128 v[140:143], v140 offset:3072
	ds_read_b128 v[156:159], v168
	ds_read_b128 v[160:163], v168 offset:1024
	ds_read_b128 v[164:167], v168 offset:2048
	ds_read_b128 v[168:171], v168 offset:3072
	v_lshl_add_u64 v[218:219], s[12:13], 0, v[154:155]
	s_add_i32 m0, s48, 0xc000
	ds_read_b128 v[172:175], v179
	ds_read_b128 v[180:183], v179 offset:1024
	ds_read_b128 v[184:187], v179 offset:2048
	ds_read_b128 v[188:191], v179 offset:3072
	ds_read_b128 v[194:197], v179 offset:4096
	ds_read_b128 v[198:201], v179 offset:5120
	ds_read_b128 v[202:205], v179 offset:6144
	ds_read_b128 v[214:217], v179 offset:7168
	global_load_lds_dwordx4 v[218:219], off
	v_lshl_add_u64 v[218:219], s[12:13], 0, v[152:153]
	s_add_i32 m0, s48, 0xe000
	s_nop 0
	global_load_lds_dwordx4 v[218:219], off
	s_waitcnt vmcnt(8)
	s_waitcnt lgkmcnt(0)
	s_barrier
	s_setprio 1
	v_mfma_f32_16x16x32_bf16 v[124:127], v[128:131], v[172:175], v[124:127]
	v_mfma_f32_16x16x32_bf16 v[120:123], v[136:139], v[172:175], v[120:123]
	v_mfma_f32_16x16x32_bf16 v[108:111], v[128:131], v[184:187], v[108:111]
	v_mfma_f32_16x16x32_bf16 v[104:107], v[136:139], v[184:187], v[104:107]
	v_mfma_f32_16x16x32_bf16 v[92:95], v[128:131], v[194:197], v[92:95]
	v_mfma_f32_16x16x32_bf16 v[88:91], v[136:139], v[194:197], v[88:91]
	v_mfma_f32_16x16x32_bf16 v[76:79], v[128:131], v[202:205], v[76:79]
	v_mfma_f32_16x16x32_bf16 v[72:75], v[136:139], v[202:205], v[72:75]
	v_mfma_f32_16x16x32_bf16 v[124:127], v[132:135], v[180:183], v[124:127]
	v_mfma_f32_16x16x32_bf16 v[120:123], v[140:143], v[180:183], v[120:123]
	v_mfma_f32_16x16x32_bf16 v[108:111], v[132:135], v[188:191], v[108:111]
	v_mfma_f32_16x16x32_bf16 v[104:107], v[140:143], v[188:191], v[104:107]
	v_mfma_f32_16x16x32_bf16 v[92:95], v[132:135], v[198:201], v[92:95]
	v_mfma_f32_16x16x32_bf16 v[88:91], v[140:143], v[198:201], v[88:91]
	v_mfma_f32_16x16x32_bf16 v[76:79], v[132:135], v[214:217], v[76:79]
	v_mfma_f32_16x16x32_bf16 v[72:75], v[140:143], v[214:217], v[72:75]
	v_mfma_f32_16x16x32_bf16 v[116:119], v[156:159], v[172:175], v[116:119]
	v_mfma_f32_16x16x32_bf16 v[112:115], v[164:167], v[172:175], v[112:115]
	v_mfma_f32_16x16x32_bf16 v[100:103], v[156:159], v[184:187], v[100:103]
	v_mfma_f32_16x16x32_bf16 v[96:99], v[164:167], v[184:187], v[96:99]
	v_mfma_f32_16x16x32_bf16 v[84:87], v[156:159], v[194:197], v[84:87]
	v_mfma_f32_16x16x32_bf16 v[80:83], v[164:167], v[194:197], v[80:83]
	v_mfma_f32_16x16x32_bf16 v[68:71], v[156:159], v[202:205], v[68:71]
	v_mfma_f32_16x16x32_bf16 v[64:67], v[164:167], v[202:205], v[64:67]
	v_mfma_f32_16x16x32_bf16 v[116:119], v[160:163], v[180:183], v[116:119]
	v_mfma_f32_16x16x32_bf16 v[112:115], v[168:171], v[180:183], v[112:115]
	v_mfma_f32_16x16x32_bf16 v[100:103], v[160:163], v[188:191], v[100:103]
	v_mfma_f32_16x16x32_bf16 v[96:99], v[168:171], v[188:191], v[96:99]
	v_mfma_f32_16x16x32_bf16 v[84:87], v[160:163], v[198:201], v[84:87]
	v_mfma_f32_16x16x32_bf16 v[80:83], v[168:171], v[198:201], v[80:83]
	v_mfma_f32_16x16x32_bf16 v[68:71], v[160:163], v[214:217], v[68:71]
	v_mfma_f32_16x16x32_bf16 v[64:67], v[168:171], v[214:217], v[64:67]
	s_setprio 0
	s_barrier
	s_add_i32 s40, s40, s61
	v_lshl_add_u64 v[218:219], s[14:15], 0, v[148:149]
	s_mov_b32 m0, s40
	ds_read_b128 v[172:175], v179 offset:16384
	ds_read_b128 v[180:183], v179 offset:17408
	ds_read_b128 v[184:187], v179 offset:18432
	ds_read_b128 v[188:191], v179 offset:19456
	ds_read_b128 v[194:197], v179 offset:20480
	ds_read_b128 v[198:201], v179 offset:21504
	ds_read_b128 v[202:205], v179 offset:22528
	ds_read_b128 v[214:217], v179 offset:23552
	global_load_lds_dwordx4 v[218:219], off
	s_add_i32 m0, s40, 0x2000
	s_add_u32 s44, s14, 0x40000
	v_lshl_add_u64 v[220:221], s[14:15], 0, v[144:145]
	s_addc_u32 s45, s15, 0
	s_add_i32 s40, s52, s61
	global_load_lds_dwordx4 v[220:221], off
	v_lshl_add_u64 v[222:223], s[44:45], 0, v[148:149]
	s_mov_b32 m0, s40
	v_lshl_add_u64 v[224:225], s[16:17], 0, v[146:147]
	global_load_lds_dwordx4 v[222:223], off
	v_lshl_add_u64 v[222:223], s[44:45], 0, v[144:145]
	s_add_i32 m0, s40, 0x2000
	s_nop 0
	global_load_lds_dwordx4 v[222:223], off
	v_lshl_add_u64 v[222:223], s[16:17], 0, v[150:151]
	s_mov_b32 m0, s48
	s_nop 0
	global_load_lds_dwordx4 v[222:223], off
	s_mov_b32 m0, s49
	s_nop 0
	global_load_lds_dwordx4 v[224:225], off
	s_waitcnt vmcnt(8)
	s_waitcnt lgkmcnt(0)
	s_barrier
	s_setprio 1
	v_mfma_f32_16x16x32_bf16 v[60:63], v[128:131], v[172:175], v[60:63]
	v_mfma_f32_16x16x32_bf16 v[56:59], v[136:139], v[172:175], v[56:59]
	v_mfma_f32_16x16x32_bf16 v[44:47], v[128:131], v[184:187], v[44:47]
	v_mfma_f32_16x16x32_bf16 v[40:43], v[136:139], v[184:187], v[40:43]
	v_mfma_f32_16x16x32_bf16 v[28:31], v[128:131], v[194:197], v[28:31]
	v_mfma_f32_16x16x32_bf16 v[24:27], v[136:139], v[194:197], v[24:27]
	v_mfma_f32_16x16x32_bf16 v[12:15], v[128:131], v[202:205], v[12:15]
	v_mfma_f32_16x16x32_bf16 v[8:11], v[136:139], v[202:205], v[8:11]
	v_mfma_f32_16x16x32_bf16 v[60:63], v[132:135], v[180:183], v[60:63]
	v_mfma_f32_16x16x32_bf16 v[56:59], v[140:143], v[180:183], v[56:59]
	v_mfma_f32_16x16x32_bf16 v[44:47], v[132:135], v[188:191], v[44:47]
	v_mfma_f32_16x16x32_bf16 v[40:43], v[140:143], v[188:191], v[40:43]
	v_mfma_f32_16x16x32_bf16 v[28:31], v[132:135], v[198:201], v[28:31]
	v_mfma_f32_16x16x32_bf16 v[24:27], v[140:143], v[198:201], v[24:27]
	v_mfma_f32_16x16x32_bf16 v[12:15], v[132:135], v[214:217], v[12:15]
	v_mfma_f32_16x16x32_bf16 v[8:11], v[140:143], v[214:217], v[8:11]
	v_mfma_f32_16x16x32_bf16 v[52:55], v[156:159], v[172:175], v[52:55]
	v_mfma_f32_16x16x32_bf16 v[48:51], v[164:167], v[172:175], v[48:51]
	v_mfma_f32_16x16x32_bf16 v[36:39], v[156:159], v[184:187], v[36:39]
	v_mfma_f32_16x16x32_bf16 v[32:35], v[164:167], v[184:187], v[32:35]
	v_mfma_f32_16x16x32_bf16 v[20:23], v[156:159], v[194:197], v[20:23]
	v_mfma_f32_16x16x32_bf16 v[16:19], v[164:167], v[194:197], v[16:19]
	v_mfma_f32_16x16x32_bf16 v[4:7], v[156:159], v[202:205], v[4:7]
	v_mfma_f32_16x16x32_bf16 v[0:3], v[164:167], v[202:205], v[0:3]
	v_mfma_f32_16x16x32_bf16 v[52:55], v[160:163], v[180:183], v[52:55]
	v_mfma_f32_16x16x32_bf16 v[48:51], v[168:171], v[180:183], v[48:51]
	v_mfma_f32_16x16x32_bf16 v[36:39], v[160:163], v[188:191], v[36:39]
	v_mfma_f32_16x16x32_bf16 v[32:35], v[168:171], v[188:191], v[32:35]
	v_mfma_f32_16x16x32_bf16 v[20:23], v[160:163], v[198:201], v[20:23]
	v_mfma_f32_16x16x32_bf16 v[16:19], v[168:171], v[198:201], v[16:19]
	v_mfma_f32_16x16x32_bf16 v[4:7], v[160:163], v[214:217], v[4:7]
	v_mfma_f32_16x16x32_bf16 v[0:3], v[168:171], v[214:217], v[0:3]
	s_setprio 0
	s_barrier
	s_add_i32 s40, 0, 0x18000
	s_add_i32 s44, 0, 0x1c000
	v_add_u32_e32 v140, s40, v178
	v_add_u32_e32 v168, s44, v178
	ds_read_b128 v[128:131], v140
	ds_read_b128 v[132:135], v140 offset:1024
	ds_read_b128 v[136:139], v140 offset:2048
	ds_read_b128 v[140:143], v140 offset:3072
	ds_read_b128 v[156:159], v168
	ds_read_b128 v[160:163], v168 offset:1024
	ds_read_b128 v[164:167], v168 offset:2048
	ds_read_b128 v[168:171], v168 offset:3072
	s_add_u32 s16, s16, 0x40000
	s_addc_u32 s17, s17, 0
	s_mov_b32 m0, s58
	v_lshl_add_u64 v[226:227], s[16:17], 0, v[150:151]
	ds_read_b128 v[172:175], v179 offset:32768
	ds_read_b128 v[180:183], v179 offset:33792
	ds_read_b128 v[184:187], v179 offset:34816
	ds_read_b128 v[188:191], v179 offset:35840
	ds_read_b128 v[194:197], v179 offset:36864
	ds_read_b128 v[198:201], v179 offset:37888
	ds_read_b128 v[202:205], v179 offset:38912
	ds_read_b128 v[214:217], v179 offset:39936
	global_load_lds_dwordx4 v[226:227], off
	v_lshl_add_u64 v[226:227], s[16:17], 0, v[146:147]
	s_mov_b32 m0, s59
	s_nop 0
	global_load_lds_dwordx4 v[226:227], off
	s_waitcnt vmcnt(8)
	s_waitcnt lgkmcnt(0)
	s_barrier
	s_setprio 1
	v_mfma_f32_16x16x32_bf16 v[124:127], v[128:131], v[172:175], v[124:127]
	v_mfma_f32_16x16x32_bf16 v[120:123], v[136:139], v[172:175], v[120:123]
	v_mfma_f32_16x16x32_bf16 v[108:111], v[128:131], v[184:187], v[108:111]
	v_mfma_f32_16x16x32_bf16 v[104:107], v[136:139], v[184:187], v[104:107]
	v_mfma_f32_16x16x32_bf16 v[92:95], v[128:131], v[194:197], v[92:95]
	v_mfma_f32_16x16x32_bf16 v[88:91], v[136:139], v[194:197], v[88:91]
	v_mfma_f32_16x16x32_bf16 v[76:79], v[128:131], v[202:205], v[76:79]
	v_mfma_f32_16x16x32_bf16 v[72:75], v[136:139], v[202:205], v[72:75]
	v_mfma_f32_16x16x32_bf16 v[124:127], v[132:135], v[180:183], v[124:127]
	v_mfma_f32_16x16x32_bf16 v[120:123], v[140:143], v[180:183], v[120:123]
	v_mfma_f32_16x16x32_bf16 v[108:111], v[132:135], v[188:191], v[108:111]
	v_mfma_f32_16x16x32_bf16 v[104:107], v[140:143], v[188:191], v[104:107]
	v_mfma_f32_16x16x32_bf16 v[92:95], v[132:135], v[198:201], v[92:95]
	v_mfma_f32_16x16x32_bf16 v[88:91], v[140:143], v[198:201], v[88:91]
	v_mfma_f32_16x16x32_bf16 v[76:79], v[132:135], v[214:217], v[76:79]
	v_mfma_f32_16x16x32_bf16 v[72:75], v[140:143], v[214:217], v[72:75]
	v_mfma_f32_16x16x32_bf16 v[116:119], v[156:159], v[172:175], v[116:119]
	v_mfma_f32_16x16x32_bf16 v[112:115], v[164:167], v[172:175], v[112:115]
	v_mfma_f32_16x16x32_bf16 v[100:103], v[156:159], v[184:187], v[100:103]
	v_mfma_f32_16x16x32_bf16 v[96:99], v[164:167], v[184:187], v[96:99]
	v_mfma_f32_16x16x32_bf16 v[84:87], v[156:159], v[194:197], v[84:87]
	v_mfma_f32_16x16x32_bf16 v[80:83], v[164:167], v[194:197], v[80:83]
	v_mfma_f32_16x16x32_bf16 v[68:71], v[156:159], v[202:205], v[68:71]
	v_mfma_f32_16x16x32_bf16 v[64:67], v[164:167], v[202:205], v[64:67]
	v_mfma_f32_16x16x32_bf16 v[116:119], v[160:163], v[180:183], v[116:119]
	v_mfma_f32_16x16x32_bf16 v[112:115], v[168:171], v[180:183], v[112:115]
	v_mfma_f32_16x16x32_bf16 v[100:103], v[160:163], v[188:191], v[100:103]
	v_mfma_f32_16x16x32_bf16 v[96:99], v[168:171], v[188:191], v[96:99]
	v_mfma_f32_16x16x32_bf16 v[84:87], v[160:163], v[198:201], v[84:87]
	v_mfma_f32_16x16x32_bf16 v[80:83], v[168:171], v[198:201], v[80:83]
	v_mfma_f32_16x16x32_bf16 v[68:71], v[160:163], v[214:217], v[68:71]
	v_mfma_f32_16x16x32_bf16 v[64:67], v[168:171], v[214:217], v[64:67]
	s_setprio 0
	s_barrier
	s_add_i32 s16, s40, s61
	v_lshl_add_u64 v[218:219], v[218:219], 0, s[76:77]
	s_mov_b32 m0, s16
	ds_read_b128 v[172:175], v179 offset:49152
	ds_read_b128 v[180:183], v179 offset:50176
	ds_read_b128 v[184:187], v179 offset:51200
	ds_read_b128 v[188:191], v179 offset:52224
	ds_read_b128 v[194:197], v179 offset:53248
	ds_read_b128 v[198:201], v179 offset:54272
	ds_read_b128 v[202:205], v179 offset:55296
	ds_read_b128 v[214:217], v179 offset:56320
	global_load_lds_dwordx4 v[218:219], off
	s_add_i32 m0, s16, 0x2000
	s_add_u32 s14, s14, 0x40080
	v_lshl_add_u64 v[218:219], v[220:221], 0, s[76:77]
	s_addc_u32 s15, s15, 0
	s_add_i32 s16, s44, s61
	global_load_lds_dwordx4 v[218:219], off
	v_lshl_add_u64 v[218:219], s[14:15], 0, v[148:149]
	s_mov_b32 m0, s16
	s_nop 0
	global_load_lds_dwordx4 v[218:219], off
	v_lshl_add_u64 v[218:219], s[14:15], 0, v[144:145]
	s_add_i32 m0, s16, 0x2000
	s_nop 0
	global_load_lds_dwordx4 v[218:219], off
	v_lshl_add_u64 v[218:219], v[222:223], 0, s[76:77]
	s_mov_b32 m0, s26
	s_nop 0
	global_load_lds_dwordx4 v[218:219], off
	v_lshl_add_u64 v[218:219], v[224:225], 0, s[76:77]
	s_mov_b32 m0, s27
	s_nop 0
	global_load_lds_dwordx4 v[218:219], off
	s_waitcnt vmcnt(8)
	s_waitcnt lgkmcnt(0)
	s_barrier
	s_setprio 1
	v_mfma_f32_16x16x32_bf16 v[60:63], v[128:131], v[172:175], v[60:63]
	v_mfma_f32_16x16x32_bf16 v[56:59], v[136:139], v[172:175], v[56:59]
	v_mfma_f32_16x16x32_bf16 v[44:47], v[128:131], v[184:187], v[44:47]
	v_mfma_f32_16x16x32_bf16 v[40:43], v[136:139], v[184:187], v[40:43]
	v_mfma_f32_16x16x32_bf16 v[28:31], v[128:131], v[194:197], v[28:31]
	v_mfma_f32_16x16x32_bf16 v[24:27], v[136:139], v[194:197], v[24:27]
	v_mfma_f32_16x16x32_bf16 v[12:15], v[128:131], v[202:205], v[12:15]
	v_mfma_f32_16x16x32_bf16 v[8:11], v[136:139], v[202:205], v[8:11]
	v_mfma_f32_16x16x32_bf16 v[60:63], v[132:135], v[180:183], v[60:63]
	v_mfma_f32_16x16x32_bf16 v[56:59], v[140:143], v[180:183], v[56:59]
	v_mfma_f32_16x16x32_bf16 v[44:47], v[132:135], v[188:191], v[44:47]
	v_mfma_f32_16x16x32_bf16 v[40:43], v[140:143], v[188:191], v[40:43]
	v_mfma_f32_16x16x32_bf16 v[28:31], v[132:135], v[198:201], v[28:31]
	v_mfma_f32_16x16x32_bf16 v[24:27], v[140:143], v[198:201], v[24:27]
	v_mfma_f32_16x16x32_bf16 v[12:15], v[132:135], v[214:217], v[12:15]
	v_mfma_f32_16x16x32_bf16 v[8:11], v[140:143], v[214:217], v[8:11]
	v_mfma_f32_16x16x32_bf16 v[52:55], v[156:159], v[172:175], v[52:55]
	v_mfma_f32_16x16x32_bf16 v[48:51], v[164:167], v[172:175], v[48:51]
	v_mfma_f32_16x16x32_bf16 v[36:39], v[156:159], v[184:187], v[36:39]
	v_mfma_f32_16x16x32_bf16 v[32:35], v[164:167], v[184:187], v[32:35]
	v_mfma_f32_16x16x32_bf16 v[20:23], v[156:159], v[194:197], v[20:23]
	v_mfma_f32_16x16x32_bf16 v[16:19], v[164:167], v[194:197], v[16:19]
	v_mfma_f32_16x16x32_bf16 v[4:7], v[156:159], v[202:205], v[4:7]
	v_mfma_f32_16x16x32_bf16 v[0:3], v[164:167], v[202:205], v[0:3]
	v_mfma_f32_16x16x32_bf16 v[52:55], v[160:163], v[180:183], v[52:55]
	v_mfma_f32_16x16x32_bf16 v[48:51], v[168:171], v[180:183], v[48:51]
	v_mfma_f32_16x16x32_bf16 v[36:39], v[160:163], v[188:191], v[36:39]
	v_mfma_f32_16x16x32_bf16 v[32:35], v[168:171], v[188:191], v[32:35]
	s_add_i32 s39, s39, 2
	s_add_u32 s33, s33, 0x100
	s_addc_u32 s38, s38, 0
	s_add_u32 s12, s12, 0x100
	s_addc_u32 s13, s13, 0
	v_mfma_f32_16x16x32_bf16 v[20:23], v[160:163], v[198:201], v[20:23]
	v_mfma_f32_16x16x32_bf16 v[16:19], v[168:171], v[198:201], v[16:19]
	v_mfma_f32_16x16x32_bf16 v[4:7], v[160:163], v[214:217], v[4:7]
	v_mfma_f32_16x16x32_bf16 v[0:3], v[168:171], v[214:217], v[0:3]
	s_setprio 0
	s_barrier
	s_cmp_gt_u32 s39, 13
	s_cbranch_scc0 .LBB0_299
	s_and_b64 vcc, exec, s[80:81]
	s_cbranch_vccz .LBB0_302
	s_barrier

.LBB0_650:
	s_add_u32 s24, s22, 0x100
	s_addc_u32 s25, s23, 0
	s_add_u32 s26, s19, s22
	s_addc_u32 s27, s63, s23
	s_cmp_eq_u32 s64, 4
	s_cselect_b32 s28, 0, s24
	s_cselect_b32 s29, 0, s25
	s_cselect_b32 s26, s13, s26
	s_cselect_b32 s27, s11, s27
	s_add_u32 s28, s2, s28
	s_addc_u32 s29, s3, s29
	s_add_i32 s65, 0, 0x10000
	s_add_i32 s66, 0, 0x14000
	v_add_u32_e32 v140, s65, v166
	v_add_u32_e32 v172, s66, v166
	ds_read_b128 v[128:131], v140
	ds_read_b128 v[132:135], v140 offset:1024
	ds_read_b128 v[136:139], v140 offset:2048
	ds_read_b128 v[140:143], v140 offset:3072
	ds_read_b128 v[144:147], v172
	ds_read_b128 v[148:151], v172 offset:1024
	ds_read_b128 v[168:171], v172 offset:2048
	ds_read_b128 v[172:175], v172 offset:3072
	v_lshl_add_u64 v[218:219], v[162:163], 0, s[22:23]
	s_add_i32 m0, s21, 0xc000
	ds_read_b128 v[176:179], v167
	ds_read_b128 v[180:183], v167 offset:1024
	ds_read_b128 v[184:187], v167 offset:2048
	ds_read_b128 v[188:191], v167 offset:3072
	ds_read_b128 v[194:197], v167 offset:4096
	ds_read_b128 v[198:201], v167 offset:5120
	ds_read_b128 v[202:205], v167 offset:6144
	ds_read_b128 v[214:217], v167 offset:7168
	global_load_lds_dwordx4 v[218:219], off
	v_lshl_add_u64 v[218:219], v[160:161], 0, s[22:23]
	s_add_i32 m0, s21, 0xe000
	s_nop 0
	global_load_lds_dwordx4 v[218:219], off
	s_waitcnt vmcnt(8)
	s_waitcnt lgkmcnt(0)
	s_barrier
	s_setprio 1
	v_mfma_f32_16x16x32_bf16 v[124:127], v[128:131], v[176:179], v[124:127]
	v_mfma_f32_16x16x32_bf16 v[120:123], v[136:139], v[176:179], v[120:123]
	v_mfma_f32_16x16x32_bf16 v[108:111], v[128:131], v[184:187], v[108:111]
	v_mfma_f32_16x16x32_bf16 v[104:107], v[136:139], v[184:187], v[104:107]
	v_mfma_f32_16x16x32_bf16 v[96:99], v[128:131], v[194:197], v[96:99]
	v_mfma_f32_16x16x32_bf16 v[88:91], v[136:139], v[194:197], v[88:91]
	v_mfma_f32_16x16x32_bf16 v[80:83], v[128:131], v[202:205], v[80:83]
	v_mfma_f32_16x16x32_bf16 v[72:75], v[136:139], v[202:205], v[72:75]
	v_mfma_f32_16x16x32_bf16 v[124:127], v[132:135], v[180:183], v[124:127]
	v_mfma_f32_16x16x32_bf16 v[120:123], v[140:143], v[180:183], v[120:123]
	v_mfma_f32_16x16x32_bf16 v[108:111], v[132:135], v[188:191], v[108:111]
	v_mfma_f32_16x16x32_bf16 v[104:107], v[140:143], v[188:191], v[104:107]
	v_mfma_f32_16x16x32_bf16 v[96:99], v[132:135], v[198:201], v[96:99]
	v_mfma_f32_16x16x32_bf16 v[88:91], v[140:143], v[198:201], v[88:91]
	v_mfma_f32_16x16x32_bf16 v[80:83], v[132:135], v[214:217], v[80:83]
	v_mfma_f32_16x16x32_bf16 v[72:75], v[140:143], v[214:217], v[72:75]
	v_mfma_f32_16x16x32_bf16 v[116:119], v[144:147], v[176:179], v[116:119]
	v_mfma_f32_16x16x32_bf16 v[112:115], v[168:171], v[176:179], v[112:115]
	v_mfma_f32_16x16x32_bf16 v[100:103], v[144:147], v[184:187], v[100:103]
	v_mfma_f32_16x16x32_bf16 v[92:95], v[168:171], v[184:187], v[92:95]
	v_mfma_f32_16x16x32_bf16 v[84:87], v[144:147], v[194:197], v[84:87]
	v_mfma_f32_16x16x32_bf16 v[76:79], v[168:171], v[194:197], v[76:79]
	v_mfma_f32_16x16x32_bf16 v[68:71], v[144:147], v[202:205], v[68:71]
	v_mfma_f32_16x16x32_bf16 v[64:67], v[168:171], v[202:205], v[64:67]
	v_mfma_f32_16x16x32_bf16 v[116:119], v[148:151], v[180:183], v[116:119]
	v_mfma_f32_16x16x32_bf16 v[112:115], v[172:175], v[180:183], v[112:115]
	v_mfma_f32_16x16x32_bf16 v[100:103], v[148:151], v[188:191], v[100:103]
	v_mfma_f32_16x16x32_bf16 v[92:95], v[172:175], v[188:191], v[92:95]
	v_mfma_f32_16x16x32_bf16 v[84:87], v[148:151], v[198:201], v[84:87]
	v_mfma_f32_16x16x32_bf16 v[76:79], v[172:175], v[198:201], v[76:79]
	v_mfma_f32_16x16x32_bf16 v[68:71], v[148:151], v[214:217], v[68:71]
	v_mfma_f32_16x16x32_bf16 v[64:67], v[172:175], v[214:217], v[64:67]
	s_setprio 0
	s_barrier
	s_add_i32 s22, s65, s35
	v_lshl_add_u64 v[218:219], s[26:27], 0, v[156:157]
	s_mov_b32 m0, s22
	ds_read_b128 v[176:179], v167 offset:16384
	ds_read_b128 v[180:183], v167 offset:17408
	ds_read_b128 v[184:187], v167 offset:18432
	ds_read_b128 v[188:191], v167 offset:19456
	ds_read_b128 v[194:197], v167 offset:20480
	ds_read_b128 v[198:201], v167 offset:21504
	ds_read_b128 v[202:205], v167 offset:22528
	ds_read_b128 v[214:217], v167 offset:23552
	global_load_lds_dwordx4 v[218:219], off
	s_add_i32 m0, s22, 0x2000
	s_add_u32 s22, s26, 0x20000
	v_lshl_add_u64 v[220:221], s[26:27], 0, v[152:153]
	s_addc_u32 s23, s27, 0
	s_add_i32 s65, s66, s35
	global_load_lds_dwordx4 v[220:221], off
	v_lshl_add_u64 v[222:223], s[22:23], 0, v[156:157]
	s_mov_b32 m0, s65
	v_lshl_add_u64 v[224:225], s[28:29], 0, v[154:155]
	global_load_lds_dwordx4 v[222:223], off
	v_lshl_add_u64 v[222:223], s[22:23], 0, v[152:153]
	s_add_i32 m0, s65, 0x2000
	s_nop 0
	global_load_lds_dwordx4 v[222:223], off
	v_lshl_add_u64 v[222:223], s[28:29], 0, v[158:159]
	s_mov_b32 m0, s21
	s_nop 0
	global_load_lds_dwordx4 v[222:223], off
	s_mov_b32 m0, s36
	s_nop 0
	global_load_lds_dwordx4 v[224:225], off
	s_waitcnt vmcnt(8)
	s_waitcnt lgkmcnt(0)
	s_barrier
	s_setprio 1
	v_mfma_f32_16x16x32_bf16 v[60:63], v[128:131], v[176:179], v[60:63]
	v_mfma_f32_16x16x32_bf16 v[56:59], v[136:139], v[176:179], v[56:59]
	v_mfma_f32_16x16x32_bf16 v[48:51], v[128:131], v[184:187], v[48:51]
	v_mfma_f32_16x16x32_bf16 v[40:43], v[136:139], v[184:187], v[40:43]
	v_mfma_f32_16x16x32_bf16 v[32:35], v[128:131], v[194:197], v[32:35]
	v_mfma_f32_16x16x32_bf16 v[24:27], v[136:139], v[194:197], v[24:27]
	v_mfma_f32_16x16x32_bf16 v[16:19], v[128:131], v[202:205], v[16:19]
	v_mfma_f32_16x16x32_bf16 v[8:11], v[136:139], v[202:205], v[8:11]
	v_mfma_f32_16x16x32_bf16 v[60:63], v[132:135], v[180:183], v[60:63]
	v_mfma_f32_16x16x32_bf16 v[56:59], v[140:143], v[180:183], v[56:59]
	v_mfma_f32_16x16x32_bf16 v[48:51], v[132:135], v[188:191], v[48:51]
	v_mfma_f32_16x16x32_bf16 v[40:43], v[140:143], v[188:191], v[40:43]
	v_mfma_f32_16x16x32_bf16 v[32:35], v[132:135], v[198:201], v[32:35]
	v_mfma_f32_16x16x32_bf16 v[24:27], v[140:143], v[198:201], v[24:27]
	v_mfma_f32_16x16x32_bf16 v[16:19], v[132:135], v[214:217], v[16:19]
	v_mfma_f32_16x16x32_bf16 v[8:11], v[140:143], v[214:217], v[8:11]
	v_mfma_f32_16x16x32_bf16 v[52:55], v[144:147], v[176:179], v[52:55]
	v_mfma_f32_16x16x32_bf16 v[44:47], v[168:171], v[176:179], v[44:47]
	v_mfma_f32_16x16x32_bf16 v[36:39], v[144:147], v[184:187], v[36:39]
	v_mfma_f32_16x16x32_bf16 v[28:31], v[168:171], v[184:187], v[28:31]
	v_mfma_f32_16x16x32_bf16 v[20:23], v[144:147], v[194:197], v[20:23]
	v_mfma_f32_16x16x32_bf16 v[12:15], v[168:171], v[194:197], v[12:15]
	v_mfma_f32_16x16x32_bf16 v[4:7], v[144:147], v[202:205], v[4:7]
	v_mfma_f32_16x16x32_bf16 v[0:3], v[168:171], v[202:205], v[0:3]
	v_mfma_f32_16x16x32_bf16 v[52:55], v[148:151], v[180:183], v[52:55]
	v_mfma_f32_16x16x32_bf16 v[44:47], v[172:175], v[180:183], v[44:47]
	v_mfma_f32_16x16x32_bf16 v[36:39], v[148:151], v[188:191], v[36:39]
	v_mfma_f32_16x16x32_bf16 v[28:31], v[172:175], v[188:191], v[28:31]
	v_mfma_f32_16x16x32_bf16 v[20:23], v[148:151], v[198:201], v[20:23]
	v_mfma_f32_16x16x32_bf16 v[12:15], v[172:175], v[198:201], v[12:15]
	v_mfma_f32_16x16x32_bf16 v[4:7], v[148:151], v[214:217], v[4:7]
	v_mfma_f32_16x16x32_bf16 v[0:3], v[172:175], v[214:217], v[0:3]
	s_setprio 0
	s_barrier
	s_add_i32 s65, 0, 0x18000
	s_add_i32 s66, 0, 0x1c000
	v_add_u32_e32 v140, s65, v166
	v_add_u32_e32 v172, s66, v166
	ds_read_b128 v[128:131], v140
	ds_read_b128 v[132:135], v140 offset:1024
	ds_read_b128 v[136:139], v140 offset:2048
	ds_read_b128 v[140:143], v140 offset:3072
	ds_read_b128 v[144:147], v172
	ds_read_b128 v[148:151], v172 offset:1024
	ds_read_b128 v[168:171], v172 offset:2048
	ds_read_b128 v[172:175], v172 offset:3072
	s_add_u32 s22, s28, 0x20000
	s_addc_u32 s23, s29, 0
	s_mov_b32 m0, s37
	v_lshl_add_u64 v[226:227], s[22:23], 0, v[158:159]
	ds_read_b128 v[176:179], v167 offset:32768
	ds_read_b128 v[180:183], v167 offset:33792
	ds_read_b128 v[184:187], v167 offset:34816
	ds_read_b128 v[188:191], v167 offset:35840
	ds_read_b128 v[194:197], v167 offset:36864
	ds_read_b128 v[198:201], v167 offset:37888
	ds_read_b128 v[202:205], v167 offset:38912
	ds_read_b128 v[214:217], v167 offset:39936
	global_load_lds_dwordx4 v[226:227], off
	v_lshl_add_u64 v[226:227], s[22:23], 0, v[154:155]
	s_mov_b32 m0, s38
	s_nop 0
	global_load_lds_dwordx4 v[226:227], off
	s_waitcnt vmcnt(8)
	s_waitcnt lgkmcnt(0)
	s_barrier
	s_setprio 1
	v_mfma_f32_16x16x32_bf16 v[124:127], v[128:131], v[176:179], v[124:127]
	v_mfma_f32_16x16x32_bf16 v[120:123], v[136:139], v[176:179], v[120:123]
	v_mfma_f32_16x16x32_bf16 v[108:111], v[128:131], v[184:187], v[108:111]
	v_mfma_f32_16x16x32_bf16 v[104:107], v[136:139], v[184:187], v[104:107]
	v_mfma_f32_16x16x32_bf16 v[96:99], v[128:131], v[194:197], v[96:99]
	v_mfma_f32_16x16x32_bf16 v[88:91], v[136:139], v[194:197], v[88:91]
	v_mfma_f32_16x16x32_bf16 v[80:83], v[128:131], v[202:205], v[80:83]
	v_mfma_f32_16x16x32_bf16 v[72:75], v[136:139], v[202:205], v[72:75]
	v_mfma_f32_16x16x32_bf16 v[124:127], v[132:135], v[180:183], v[124:127]
	v_mfma_f32_16x16x32_bf16 v[120:123], v[140:143], v[180:183], v[120:123]
	v_mfma_f32_16x16x32_bf16 v[108:111], v[132:135], v[188:191], v[108:111]
	v_mfma_f32_16x16x32_bf16 v[104:107], v[140:143], v[188:191], v[104:107]
	v_mfma_f32_16x16x32_bf16 v[96:99], v[132:135], v[198:201], v[96:99]
	v_mfma_f32_16x16x32_bf16 v[88:91], v[140:143], v[198:201], v[88:91]
	v_mfma_f32_16x16x32_bf16 v[80:83], v[132:135], v[214:217], v[80:83]
	v_mfma_f32_16x16x32_bf16 v[72:75], v[140:143], v[214:217], v[72:75]
	v_mfma_f32_16x16x32_bf16 v[116:119], v[144:147], v[176:179], v[116:119]
	v_mfma_f32_16x16x32_bf16 v[112:115], v[168:171], v[176:179], v[112:115]
	v_mfma_f32_16x16x32_bf16 v[100:103], v[144:147], v[184:187], v[100:103]
	v_mfma_f32_16x16x32_bf16 v[92:95], v[168:171], v[184:187], v[92:95]
	v_mfma_f32_16x16x32_bf16 v[84:87], v[144:147], v[194:197], v[84:87]
	v_mfma_f32_16x16x32_bf16 v[76:79], v[168:171], v[194:197], v[76:79]
	v_mfma_f32_16x16x32_bf16 v[68:71], v[144:147], v[202:205], v[68:71]
	v_mfma_f32_16x16x32_bf16 v[64:67], v[168:171], v[202:205], v[64:67]
	v_mfma_f32_16x16x32_bf16 v[116:119], v[148:151], v[180:183], v[116:119]
	v_mfma_f32_16x16x32_bf16 v[112:115], v[172:175], v[180:183], v[112:115]
	v_mfma_f32_16x16x32_bf16 v[100:103], v[148:151], v[188:191], v[100:103]
	v_mfma_f32_16x16x32_bf16 v[92:95], v[172:175], v[188:191], v[92:95]
	v_mfma_f32_16x16x32_bf16 v[84:87], v[148:151], v[198:201], v[84:87]
	v_mfma_f32_16x16x32_bf16 v[76:79], v[172:175], v[198:201], v[76:79]
	v_mfma_f32_16x16x32_bf16 v[68:71], v[148:151], v[214:217], v[68:71]
	v_mfma_f32_16x16x32_bf16 v[64:67], v[172:175], v[214:217], v[64:67]
	s_setprio 0
	s_barrier
	s_add_i32 s22, s65, s35
	v_lshl_add_u64 v[218:219], v[218:219], 0, s[76:77]
	s_mov_b32 m0, s22
	ds_read_b128 v[176:179], v167 offset:49152
	ds_read_b128 v[180:183], v167 offset:50176
	ds_read_b128 v[184:187], v167 offset:51200
	ds_read_b128 v[188:191], v167 offset:52224
	ds_read_b128 v[194:197], v167 offset:53248
	ds_read_b128 v[198:201], v167 offset:54272
	ds_read_b128 v[202:205], v167 offset:55296
	ds_read_b128 v[214:217], v167 offset:56320
	global_load_lds_dwordx4 v[218:219], off
	s_add_i32 m0, s22, 0x2000
	s_add_u32 s22, s26, 0x20080
	v_lshl_add_u64 v[218:219], v[220:221], 0, s[76:77]
	s_addc_u32 s23, s27, 0
	s_add_i32 s26, s66, s35
	global_load_lds_dwordx4 v[218:219], off
	v_lshl_add_u64 v[218:219], s[22:23], 0, v[156:157]
	s_mov_b32 m0, s26
	s_nop 0
	global_load_lds_dwordx4 v[218:219], off
	v_lshl_add_u64 v[218:219], s[22:23], 0, v[152:153]
	s_add_i32 m0, s26, 0x2000
	s_nop 0
	global_load_lds_dwordx4 v[218:219], off
	v_lshl_add_u64 v[218:219], v[222:223], 0, s[76:77]
	s_mov_b32 m0, s44
	s_nop 0
	global_load_lds_dwordx4 v[218:219], off
	v_lshl_add_u64 v[218:219], v[224:225], 0, s[76:77]
	s_mov_b32 m0, s45
	s_nop 0
	global_load_lds_dwordx4 v[218:219], off
	s_waitcnt vmcnt(8)
	s_waitcnt lgkmcnt(0)
	s_barrier
	s_setprio 1
	v_mfma_f32_16x16x32_bf16 v[60:63], v[128:131], v[176:179], v[60:63]
	v_mfma_f32_16x16x32_bf16 v[56:59], v[136:139], v[176:179], v[56:59]
	v_mfma_f32_16x16x32_bf16 v[48:51], v[128:131], v[184:187], v[48:51]
	v_mfma_f32_16x16x32_bf16 v[40:43], v[136:139], v[184:187], v[40:43]
	v_mfma_f32_16x16x32_bf16 v[32:35], v[128:131], v[194:197], v[32:35]
	v_mfma_f32_16x16x32_bf16 v[24:27], v[136:139], v[194:197], v[24:27]
	v_mfma_f32_16x16x32_bf16 v[16:19], v[128:131], v[202:205], v[16:19]
	v_mfma_f32_16x16x32_bf16 v[8:11], v[136:139], v[202:205], v[8:11]
	v_mfma_f32_16x16x32_bf16 v[60:63], v[132:135], v[180:183], v[60:63]
	v_mfma_f32_16x16x32_bf16 v[56:59], v[140:143], v[180:183], v[56:59]
	v_mfma_f32_16x16x32_bf16 v[48:51], v[132:135], v[188:191], v[48:51]
	v_mfma_f32_16x16x32_bf16 v[40:43], v[140:143], v[188:191], v[40:43]
	v_mfma_f32_16x16x32_bf16 v[32:35], v[132:135], v[198:201], v[32:35]
	v_mfma_f32_16x16x32_bf16 v[24:27], v[140:143], v[198:201], v[24:27]
	v_mfma_f32_16x16x32_bf16 v[16:19], v[132:135], v[214:217], v[16:19]
	v_mfma_f32_16x16x32_bf16 v[8:11], v[140:143], v[214:217], v[8:11]
	v_mfma_f32_16x16x32_bf16 v[52:55], v[144:147], v[176:179], v[52:55]
	v_mfma_f32_16x16x32_bf16 v[44:47], v[168:171], v[176:179], v[44:47]
	v_mfma_f32_16x16x32_bf16 v[36:39], v[144:147], v[184:187], v[36:39]
	v_mfma_f32_16x16x32_bf16 v[28:31], v[168:171], v[184:187], v[28:31]
	v_mfma_f32_16x16x32_bf16 v[20:23], v[144:147], v[194:197], v[20:23]
	v_mfma_f32_16x16x32_bf16 v[12:15], v[168:171], v[194:197], v[12:15]
	v_mfma_f32_16x16x32_bf16 v[4:7], v[144:147], v[202:205], v[4:7]
	v_mfma_f32_16x16x32_bf16 v[0:3], v[168:171], v[202:205], v[0:3]
	v_mfma_f32_16x16x32_bf16 v[52:55], v[148:151], v[180:183], v[52:55]
	v_mfma_f32_16x16x32_bf16 v[44:47], v[172:175], v[180:183], v[44:47]
	v_mfma_f32_16x16x32_bf16 v[36:39], v[148:151], v[188:191], v[36:39]
	v_mfma_f32_16x16x32_bf16 v[28:31], v[172:175], v[188:191], v[28:31]
	s_add_i32 s64, s64, 2
	v_mfma_f32_16x16x32_bf16 v[20:23], v[148:151], v[198:201], v[20:23]
	v_mfma_f32_16x16x32_bf16 v[12:15], v[172:175], v[198:201], v[12:15]
	v_mfma_f32_16x16x32_bf16 v[4:7], v[148:151], v[214:217], v[4:7]
	v_mfma_f32_16x16x32_bf16 v[0:3], v[172:175], v[214:217], v[0:3]
	s_setprio 0
	s_barrier
	s_cmp_gt_u32 s64, 5
	s_mov_b64 s[22:23], s[24:25]
	s_cbranch_scc0 .LBB0_650
	s_and_b64 vcc, exec, s[8:9]
	s_cbranch_vccz .LBB0_653
	s_barrier

.LBB0_670:
	s_add_u32 s19, s24, 0xffe00080
	s_addc_u32 s26, s25, -1
	s_add_i32 s63, 0, 0x10000
	s_cmpk_eq_i32 s13, 0x7c
	s_cselect_b32 s29, s15, s26
	s_cselect_b32 s28, s14, s19
	s_cselect_b32 s27, s17, s11
	s_cselect_b32 s26, s16, s9
	s_add_i32 s19, 0, 0x14000
	v_add_u32_e32 v140, s63, v170
	v_add_u32_e32 v172, s19, v170
	ds_read_b128 v[128:131], v140
	ds_read_b128 v[132:135], v140 offset:1024
	ds_read_b128 v[136:139], v140 offset:2048
	ds_read_b128 v[140:143], v140 offset:3072
	ds_read_b128 v[144:147], v172
	ds_read_b128 v[148:151], v172 offset:1024
	ds_read_b128 v[152:155], v172 offset:2048
	ds_read_b128 v[172:175], v172 offset:3072
	v_lshl_add_u64 v[218:219], s[24:25], 0, v[166:167]
	s_add_i32 m0, s23, 0xc000
	ds_read_b128 v[176:179], v171
	ds_read_b128 v[180:183], v171 offset:1024
	ds_read_b128 v[184:187], v171 offset:2048
	ds_read_b128 v[188:191], v171 offset:3072
	ds_read_b128 v[194:197], v171 offset:4096
	ds_read_b128 v[198:201], v171 offset:5120
	ds_read_b128 v[202:205], v171 offset:6144
	ds_read_b128 v[214:217], v171 offset:7168
	global_load_lds_dwordx4 v[218:219], off
	v_lshl_add_u64 v[218:219], s[24:25], 0, v[164:165]
	s_add_i32 m0, s23, 0xe000
	s_nop 0
	global_load_lds_dwordx4 v[218:219], off
	s_waitcnt vmcnt(8)
	s_waitcnt lgkmcnt(0)
	s_barrier
	s_setprio 1
	v_mfma_f32_16x16x32_bf16 v[124:127], v[128:131], v[176:179], v[124:127]
	v_mfma_f32_16x16x32_bf16 v[120:123], v[136:139], v[176:179], v[120:123]
	v_mfma_f32_16x16x32_bf16 v[108:111], v[128:131], v[184:187], v[108:111]
	v_mfma_f32_16x16x32_bf16 v[104:107], v[136:139], v[184:187], v[104:107]
	v_mfma_f32_16x16x32_bf16 v[96:99], v[128:131], v[194:197], v[96:99]
	v_mfma_f32_16x16x32_bf16 v[88:91], v[136:139], v[194:197], v[88:91]
	v_mfma_f32_16x16x32_bf16 v[80:83], v[128:131], v[202:205], v[80:83]
	v_mfma_f32_16x16x32_bf16 v[72:75], v[136:139], v[202:205], v[72:75]
	v_mfma_f32_16x16x32_bf16 v[124:127], v[132:135], v[180:183], v[124:127]
	v_mfma_f32_16x16x32_bf16 v[120:123], v[140:143], v[180:183], v[120:123]
	v_mfma_f32_16x16x32_bf16 v[108:111], v[132:135], v[188:191], v[108:111]
	v_mfma_f32_16x16x32_bf16 v[104:107], v[140:143], v[188:191], v[104:107]
	v_mfma_f32_16x16x32_bf16 v[96:99], v[132:135], v[198:201], v[96:99]
	v_mfma_f32_16x16x32_bf16 v[88:91], v[140:143], v[198:201], v[88:91]
	v_mfma_f32_16x16x32_bf16 v[80:83], v[132:135], v[214:217], v[80:83]
	v_mfma_f32_16x16x32_bf16 v[72:75], v[140:143], v[214:217], v[72:75]
	v_mfma_f32_16x16x32_bf16 v[116:119], v[144:147], v[176:179], v[116:119]
	v_mfma_f32_16x16x32_bf16 v[112:115], v[152:155], v[176:179], v[112:115]
	v_mfma_f32_16x16x32_bf16 v[100:103], v[144:147], v[184:187], v[100:103]
	v_mfma_f32_16x16x32_bf16 v[92:95], v[152:155], v[184:187], v[92:95]
	v_mfma_f32_16x16x32_bf16 v[84:87], v[144:147], v[194:197], v[84:87]
	v_mfma_f32_16x16x32_bf16 v[76:79], v[152:155], v[194:197], v[76:79]
	v_mfma_f32_16x16x32_bf16 v[68:71], v[144:147], v[202:205], v[68:71]
	v_mfma_f32_16x16x32_bf16 v[64:67], v[152:155], v[202:205], v[64:67]
	v_mfma_f32_16x16x32_bf16 v[116:119], v[148:151], v[180:183], v[116:119]
	v_mfma_f32_16x16x32_bf16 v[112:115], v[172:175], v[180:183], v[112:115]
	v_mfma_f32_16x16x32_bf16 v[100:103], v[148:151], v[188:191], v[100:103]
	v_mfma_f32_16x16x32_bf16 v[92:95], v[172:175], v[188:191], v[92:95]
	v_mfma_f32_16x16x32_bf16 v[84:87], v[148:151], v[198:201], v[84:87]
	v_mfma_f32_16x16x32_bf16 v[76:79], v[172:175], v[198:201], v[76:79]
	v_mfma_f32_16x16x32_bf16 v[68:71], v[148:151], v[214:217], v[68:71]
	v_mfma_f32_16x16x32_bf16 v[64:67], v[172:175], v[214:217], v[64:67]
	s_setprio 0
	s_barrier
	s_add_i32 s63, s63, s36
	v_lshl_add_u64 v[218:219], s[26:27], 0, v[160:161]
	s_mov_b32 m0, s63
	ds_read_b128 v[176:179], v171 offset:16384
	ds_read_b128 v[180:183], v171 offset:17408
	ds_read_b128 v[184:187], v171 offset:18432
	ds_read_b128 v[188:191], v171 offset:19456
	ds_read_b128 v[194:197], v171 offset:20480
	ds_read_b128 v[198:201], v171 offset:21504
	ds_read_b128 v[202:205], v171 offset:22528
	ds_read_b128 v[214:217], v171 offset:23552
	global_load_lds_dwordx4 v[218:219], off
	s_add_i32 m0, s63, 0x2000
	s_add_u32 s64, s26, 0x200000
	v_lshl_add_u64 v[220:221], s[26:27], 0, v[156:157]
	s_addc_u32 s65, s27, 0
	s_add_i32 s19, s19, s36
	global_load_lds_dwordx4 v[220:221], off
	v_lshl_add_u64 v[222:223], s[64:65], 0, v[160:161]
	s_mov_b32 m0, s19
	v_lshl_add_u64 v[224:225], s[28:29], 0, v[158:159]
	global_load_lds_dwordx4 v[222:223], off
	v_lshl_add_u64 v[222:223], s[64:65], 0, v[156:157]
	s_add_i32 m0, s19, 0x2000
	s_nop 0
	global_load_lds_dwordx4 v[222:223], off
	v_lshl_add_u64 v[222:223], s[28:29], 0, v[162:163]
	s_mov_b32 m0, s23
	s_nop 0
	global_load_lds_dwordx4 v[222:223], off
	s_mov_b32 m0, s21
	s_nop 0
	global_load_lds_dwordx4 v[224:225], off
	s_waitcnt vmcnt(8)
	s_waitcnt lgkmcnt(0)
	s_barrier
	s_setprio 1
	v_mfma_f32_16x16x32_bf16 v[60:63], v[128:131], v[176:179], v[60:63]
	v_mfma_f32_16x16x32_bf16 v[56:59], v[136:139], v[176:179], v[56:59]
	v_mfma_f32_16x16x32_bf16 v[48:51], v[128:131], v[184:187], v[48:51]
	v_mfma_f32_16x16x32_bf16 v[40:43], v[136:139], v[184:187], v[40:43]
	v_mfma_f32_16x16x32_bf16 v[32:35], v[128:131], v[194:197], v[32:35]
	v_mfma_f32_16x16x32_bf16 v[24:27], v[136:139], v[194:197], v[24:27]
	v_mfma_f32_16x16x32_bf16 v[16:19], v[128:131], v[202:205], v[16:19]
	v_mfma_f32_16x16x32_bf16 v[8:11], v[136:139], v[202:205], v[8:11]
	v_mfma_f32_16x16x32_bf16 v[60:63], v[132:135], v[180:183], v[60:63]
	v_mfma_f32_16x16x32_bf16 v[56:59], v[140:143], v[180:183], v[56:59]
	v_mfma_f32_16x16x32_bf16 v[48:51], v[132:135], v[188:191], v[48:51]
	v_mfma_f32_16x16x32_bf16 v[40:43], v[140:143], v[188:191], v[40:43]
	v_mfma_f32_16x16x32_bf16 v[32:35], v[132:135], v[198:201], v[32:35]
	v_mfma_f32_16x16x32_bf16 v[24:27], v[140:143], v[198:201], v[24:27]
	v_mfma_f32_16x16x32_bf16 v[16:19], v[132:135], v[214:217], v[16:19]
	v_mfma_f32_16x16x32_bf16 v[8:11], v[140:143], v[214:217], v[8:11]
	v_mfma_f32_16x16x32_bf16 v[52:55], v[144:147], v[176:179], v[52:55]
	v_mfma_f32_16x16x32_bf16 v[44:47], v[152:155], v[176:179], v[44:47]
	v_mfma_f32_16x16x32_bf16 v[36:39], v[144:147], v[184:187], v[36:39]
	v_mfma_f32_16x16x32_bf16 v[28:31], v[152:155], v[184:187], v[28:31]
	v_mfma_f32_16x16x32_bf16 v[20:23], v[144:147], v[194:197], v[20:23]
	v_mfma_f32_16x16x32_bf16 v[12:15], v[152:155], v[194:197], v[12:15]
	v_mfma_f32_16x16x32_bf16 v[4:7], v[144:147], v[202:205], v[4:7]
	v_mfma_f32_16x16x32_bf16 v[0:3], v[152:155], v[202:205], v[0:3]
	v_mfma_f32_16x16x32_bf16 v[52:55], v[148:151], v[180:183], v[52:55]
	v_mfma_f32_16x16x32_bf16 v[44:47], v[172:175], v[180:183], v[44:47]
	v_mfma_f32_16x16x32_bf16 v[36:39], v[148:151], v[188:191], v[36:39]
	v_mfma_f32_16x16x32_bf16 v[28:31], v[172:175], v[188:191], v[28:31]
	v_mfma_f32_16x16x32_bf16 v[20:23], v[148:151], v[198:201], v[20:23]
	v_mfma_f32_16x16x32_bf16 v[12:15], v[172:175], v[198:201], v[12:15]
	v_mfma_f32_16x16x32_bf16 v[4:7], v[148:151], v[214:217], v[4:7]
	v_mfma_f32_16x16x32_bf16 v[0:3], v[172:175], v[214:217], v[0:3]
	s_setprio 0
	s_barrier
	s_add_i32 s19, 0, 0x18000
	s_add_i32 s63, 0, 0x1c000
	v_add_u32_e32 v140, s19, v170
	v_add_u32_e32 v172, s63, v170
	ds_read_b128 v[128:131], v140
	ds_read_b128 v[132:135], v140 offset:1024
	ds_read_b128 v[136:139], v140 offset:2048
	ds_read_b128 v[140:143], v140 offset:3072
	ds_read_b128 v[144:147], v172
	ds_read_b128 v[148:151], v172 offset:1024
	ds_read_b128 v[152:155], v172 offset:2048
	ds_read_b128 v[172:175], v172 offset:3072
	s_add_u32 s28, s28, 0x200000
	s_addc_u32 s29, s29, 0
	s_mov_b32 m0, s37
	v_lshl_add_u64 v[226:227], s[28:29], 0, v[162:163]
	ds_read_b128 v[176:179], v171 offset:32768
	ds_read_b128 v[180:183], v171 offset:33792
	ds_read_b128 v[184:187], v171 offset:34816
	ds_read_b128 v[188:191], v171 offset:35840
	ds_read_b128 v[194:197], v171 offset:36864
	ds_read_b128 v[198:201], v171 offset:37888
	ds_read_b128 v[202:205], v171 offset:38912
	ds_read_b128 v[214:217], v171 offset:39936
	global_load_lds_dwordx4 v[226:227], off
	v_lshl_add_u64 v[226:227], s[28:29], 0, v[158:159]
	s_mov_b32 m0, s38
	s_nop 0
	global_load_lds_dwordx4 v[226:227], off
	s_waitcnt vmcnt(8)
	s_waitcnt lgkmcnt(0)
	s_barrier
	s_setprio 1
	v_mfma_f32_16x16x32_bf16 v[124:127], v[128:131], v[176:179], v[124:127]
	v_mfma_f32_16x16x32_bf16 v[120:123], v[136:139], v[176:179], v[120:123]
	v_mfma_f32_16x16x32_bf16 v[108:111], v[128:131], v[184:187], v[108:111]
	v_mfma_f32_16x16x32_bf16 v[104:107], v[136:139], v[184:187], v[104:107]
	v_mfma_f32_16x16x32_bf16 v[96:99], v[128:131], v[194:197], v[96:99]
	v_mfma_f32_16x16x32_bf16 v[88:91], v[136:139], v[194:197], v[88:91]
	v_mfma_f32_16x16x32_bf16 v[80:83], v[128:131], v[202:205], v[80:83]
	v_mfma_f32_16x16x32_bf16 v[72:75], v[136:139], v[202:205], v[72:75]
	v_mfma_f32_16x16x32_bf16 v[124:127], v[132:135], v[180:183], v[124:127]
	v_mfma_f32_16x16x32_bf16 v[120:123], v[140:143], v[180:183], v[120:123]
	v_mfma_f32_16x16x32_bf16 v[108:111], v[132:135], v[188:191], v[108:111]
	v_mfma_f32_16x16x32_bf16 v[104:107], v[140:143], v[188:191], v[104:107]
	v_mfma_f32_16x16x32_bf16 v[96:99], v[132:135], v[198:201], v[96:99]
	v_mfma_f32_16x16x32_bf16 v[88:91], v[140:143], v[198:201], v[88:91]
	v_mfma_f32_16x16x32_bf16 v[80:83], v[132:135], v[214:217], v[80:83]
	v_mfma_f32_16x16x32_bf16 v[72:75], v[140:143], v[214:217], v[72:75]
	v_mfma_f32_16x16x32_bf16 v[116:119], v[144:147], v[176:179], v[116:119]
	v_mfma_f32_16x16x32_bf16 v[112:115], v[152:155], v[176:179], v[112:115]
	v_mfma_f32_16x16x32_bf16 v[100:103], v[144:147], v[184:187], v[100:103]
	v_mfma_f32_16x16x32_bf16 v[92:95], v[152:155], v[184:187], v[92:95]
	v_mfma_f32_16x16x32_bf16 v[84:87], v[144:147], v[194:197], v[84:87]
	v_mfma_f32_16x16x32_bf16 v[76:79], v[152:155], v[194:197], v[76:79]
	v_mfma_f32_16x16x32_bf16 v[68:71], v[144:147], v[202:205], v[68:71]
	v_mfma_f32_16x16x32_bf16 v[64:67], v[152:155], v[202:205], v[64:67]
	v_mfma_f32_16x16x32_bf16 v[116:119], v[148:151], v[180:183], v[116:119]
	v_mfma_f32_16x16x32_bf16 v[112:115], v[172:175], v[180:183], v[112:115]
	v_mfma_f32_16x16x32_bf16 v[100:103], v[148:151], v[188:191], v[100:103]
	v_mfma_f32_16x16x32_bf16 v[92:95], v[172:175], v[188:191], v[92:95]
	v_mfma_f32_16x16x32_bf16 v[84:87], v[148:151], v[198:201], v[84:87]
	v_mfma_f32_16x16x32_bf16 v[76:79], v[172:175], v[198:201], v[76:79]
	v_mfma_f32_16x16x32_bf16 v[68:71], v[148:151], v[214:217], v[68:71]
	v_mfma_f32_16x16x32_bf16 v[64:67], v[172:175], v[214:217], v[64:67]
	s_setprio 0
	s_barrier
	s_add_i32 s19, s19, s36
	v_lshl_add_u64 v[218:219], v[218:219], 0, s[76:77]
	s_mov_b32 m0, s19
	ds_read_b128 v[176:179], v171 offset:49152
	ds_read_b128 v[180:183], v171 offset:50176
	ds_read_b128 v[184:187], v171 offset:51200
	ds_read_b128 v[188:191], v171 offset:52224
	ds_read_b128 v[194:197], v171 offset:53248
	ds_read_b128 v[198:201], v171 offset:54272
	ds_read_b128 v[202:205], v171 offset:55296
	ds_read_b128 v[214:217], v171 offset:56320
	global_load_lds_dwordx4 v[218:219], off
	s_add_i32 m0, s19, 0x2000
	s_add_u32 s26, s26, 0x200080
	v_lshl_add_u64 v[218:219], v[220:221], 0, s[76:77]
	s_addc_u32 s27, s27, 0
	s_add_i32 s19, s63, s36
	global_load_lds_dwordx4 v[218:219], off
	v_lshl_add_u64 v[218:219], s[26:27], 0, v[160:161]
	s_mov_b32 m0, s19
	s_nop 0
	global_load_lds_dwordx4 v[218:219], off
	v_lshl_add_u64 v[218:219], s[26:27], 0, v[156:157]
	s_add_i32 m0, s19, 0x2000
	s_nop 0
	global_load_lds_dwordx4 v[218:219], off
	v_lshl_add_u64 v[218:219], v[222:223], 0, s[76:77]
	s_mov_b32 m0, s44
	s_nop 0
	global_load_lds_dwordx4 v[218:219], off
	v_lshl_add_u64 v[218:219], v[224:225], 0, s[76:77]
	s_mov_b32 m0, s45
	s_nop 0
	global_load_lds_dwordx4 v[218:219], off
	s_waitcnt vmcnt(8)
	s_waitcnt lgkmcnt(0)
	s_barrier
	s_setprio 1
	v_mfma_f32_16x16x32_bf16 v[60:63], v[128:131], v[176:179], v[60:63]
	v_mfma_f32_16x16x32_bf16 v[56:59], v[136:139], v[176:179], v[56:59]
	v_mfma_f32_16x16x32_bf16 v[48:51], v[128:131], v[184:187], v[48:51]
	v_mfma_f32_16x16x32_bf16 v[40:43], v[136:139], v[184:187], v[40:43]
	v_mfma_f32_16x16x32_bf16 v[32:35], v[128:131], v[194:197], v[32:35]
	v_mfma_f32_16x16x32_bf16 v[24:27], v[136:139], v[194:197], v[24:27]
	v_mfma_f32_16x16x32_bf16 v[16:19], v[128:131], v[202:205], v[16:19]
	v_mfma_f32_16x16x32_bf16 v[8:11], v[136:139], v[202:205], v[8:11]
	v_mfma_f32_16x16x32_bf16 v[60:63], v[132:135], v[180:183], v[60:63]
	v_mfma_f32_16x16x32_bf16 v[56:59], v[140:143], v[180:183], v[56:59]
	v_mfma_f32_16x16x32_bf16 v[48:51], v[132:135], v[188:191], v[48:51]
	v_mfma_f32_16x16x32_bf16 v[40:43], v[140:143], v[188:191], v[40:43]
	v_mfma_f32_16x16x32_bf16 v[32:35], v[132:135], v[198:201], v[32:35]
	v_mfma_f32_16x16x32_bf16 v[24:27], v[140:143], v[198:201], v[24:27]
	v_mfma_f32_16x16x32_bf16 v[16:19], v[132:135], v[214:217], v[16:19]
	v_mfma_f32_16x16x32_bf16 v[8:11], v[140:143], v[214:217], v[8:11]
	v_mfma_f32_16x16x32_bf16 v[52:55], v[144:147], v[176:179], v[52:55]
	v_mfma_f32_16x16x32_bf16 v[44:47], v[152:155], v[176:179], v[44:47]
	v_mfma_f32_16x16x32_bf16 v[36:39], v[144:147], v[184:187], v[36:39]
	v_mfma_f32_16x16x32_bf16 v[28:31], v[152:155], v[184:187], v[28:31]
	v_mfma_f32_16x16x32_bf16 v[20:23], v[144:147], v[194:197], v[20:23]
	v_mfma_f32_16x16x32_bf16 v[12:15], v[152:155], v[194:197], v[12:15]
	v_mfma_f32_16x16x32_bf16 v[4:7], v[144:147], v[202:205], v[4:7]
	v_mfma_f32_16x16x32_bf16 v[0:3], v[152:155], v[202:205], v[0:3]
	v_mfma_f32_16x16x32_bf16 v[52:55], v[148:151], v[180:183], v[52:55]
	v_mfma_f32_16x16x32_bf16 v[44:47], v[172:175], v[180:183], v[44:47]
	v_mfma_f32_16x16x32_bf16 v[36:39], v[148:151], v[188:191], v[36:39]
	v_mfma_f32_16x16x32_bf16 v[28:31], v[172:175], v[188:191], v[28:31]
	s_add_i32 s13, s13, 2
	s_add_u32 s9, s9, 0x100
	s_addc_u32 s11, s11, 0
	s_add_u32 s24, s24, 0x100
	s_addc_u32 s25, s25, 0
	v_mfma_f32_16x16x32_bf16 v[20:23], v[148:151], v[198:201], v[20:23]
	v_mfma_f32_16x16x32_bf16 v[12:15], v[172:175], v[198:201], v[12:15]
	v_mfma_f32_16x16x32_bf16 v[4:7], v[148:151], v[214:217], v[4:7]
	v_mfma_f32_16x16x32_bf16 v[0:3], v[172:175], v[214:217], v[0:3]
	s_setprio 0
	s_barrier
	s_cmpk_gt_u32 s13, 0x7d
	s_cbranch_scc0 .LBB0_670
	s_and_b64 vcc, exec, s[4:5]
	s_cbranch_vccz .LBB0_673
	s_barrier

.LBB0_1021:
	s_add_i32 s64, s63, 2
	s_add_u32 s14, s12, 0x100
	s_addc_u32 s15, s13, 0
	s_add_i32 s65, 0, 0x10000
	s_cmp_eq_u32 s63, 38
	s_cselect_b32 s19, s9, s15
	s_cselect_b32 s18, s8, s14
	s_cselect_b32 s17, s11, s61
	s_cselect_b32 s16, s10, s60
	s_add_i32 s66, 0, 0x14000
	v_add_u32_e32 v140, s65, v222
	v_add_u32_e32 v156, s66, v222
	ds_read_b128 v[128:131], v140
	ds_read_b128 v[132:135], v140 offset:1024
	ds_read_b128 v[136:139], v140 offset:2048
	ds_read_b128 v[140:143], v140 offset:3072
	ds_read_b128 v[144:147], v156
	ds_read_b128 v[148:151], v156 offset:1024
	ds_read_b128 v[152:155], v156 offset:2048
	ds_read_b128 v[156:159], v156 offset:3072
	v_lshl_add_u64 v[228:229], s[12:13], 0, v[204:205]
	s_add_i32 m0, s26, 0xc000
	ds_read_b128 v[160:163], v225
	ds_read_b128 v[164:167], v225 offset:1024
	ds_read_b128 v[168:171], v225 offset:2048
	ds_read_b128 v[172:175], v225 offset:3072
	ds_read_b128 v[176:179], v225 offset:4096
	ds_read_b128 v[180:183], v225 offset:5120
	ds_read_b128 v[184:187], v225 offset:6144
	ds_read_b128 v[188:191], v225 offset:7168
	global_load_lds_dwordx4 v[228:229], off
	v_lshl_add_u64 v[228:229], s[12:13], 0, v[202:203]
	s_add_i32 m0, s26, 0xe000
	s_nop 0
	global_load_lds_dwordx4 v[228:229], off
	s_waitcnt vmcnt(8)
	s_waitcnt lgkmcnt(0)
	s_barrier
	s_setprio 1
	v_mfma_f32_16x16x32_bf16 v[124:127], v[128:131], v[160:163], v[124:127]
	v_mfma_f32_16x16x32_bf16 v[120:123], v[136:139], v[160:163], v[120:123]
	v_mfma_f32_16x16x32_bf16 v[108:111], v[128:131], v[168:171], v[108:111]
	v_mfma_f32_16x16x32_bf16 v[104:107], v[136:139], v[168:171], v[104:107]
	v_mfma_f32_16x16x32_bf16 v[92:95], v[128:131], v[176:179], v[92:95]
	v_mfma_f32_16x16x32_bf16 v[88:91], v[136:139], v[176:179], v[88:91]
	v_mfma_f32_16x16x32_bf16 v[76:79], v[128:131], v[184:187], v[76:79]
	v_mfma_f32_16x16x32_bf16 v[72:75], v[136:139], v[184:187], v[72:75]
	v_mfma_f32_16x16x32_bf16 v[124:127], v[132:135], v[164:167], v[124:127]
	v_mfma_f32_16x16x32_bf16 v[120:123], v[140:143], v[164:167], v[120:123]
	v_mfma_f32_16x16x32_bf16 v[108:111], v[132:135], v[172:175], v[108:111]
	v_mfma_f32_16x16x32_bf16 v[104:107], v[140:143], v[172:175], v[104:107]
	v_mfma_f32_16x16x32_bf16 v[92:95], v[132:135], v[180:183], v[92:95]
	v_mfma_f32_16x16x32_bf16 v[88:91], v[140:143], v[180:183], v[88:91]
	v_mfma_f32_16x16x32_bf16 v[76:79], v[132:135], v[188:191], v[76:79]
	v_mfma_f32_16x16x32_bf16 v[72:75], v[140:143], v[188:191], v[72:75]
	v_mfma_f32_16x16x32_bf16 v[116:119], v[144:147], v[160:163], v[116:119]
	v_mfma_f32_16x16x32_bf16 v[112:115], v[152:155], v[160:163], v[112:115]
	v_mfma_f32_16x16x32_bf16 v[100:103], v[144:147], v[168:171], v[100:103]
	v_mfma_f32_16x16x32_bf16 v[96:99], v[152:155], v[168:171], v[96:99]
	v_mfma_f32_16x16x32_bf16 v[84:87], v[144:147], v[176:179], v[84:87]
	v_mfma_f32_16x16x32_bf16 v[80:83], v[152:155], v[176:179], v[80:83]
	v_mfma_f32_16x16x32_bf16 v[68:71], v[144:147], v[184:187], v[68:71]
	v_mfma_f32_16x16x32_bf16 v[64:67], v[152:155], v[184:187], v[64:67]
	v_mfma_f32_16x16x32_bf16 v[116:119], v[148:151], v[164:167], v[116:119]
	v_mfma_f32_16x16x32_bf16 v[112:115], v[156:159], v[164:167], v[112:115]
	v_mfma_f32_16x16x32_bf16 v[100:103], v[148:151], v[172:175], v[100:103]
	v_mfma_f32_16x16x32_bf16 v[96:99], v[156:159], v[172:175], v[96:99]
	v_mfma_f32_16x16x32_bf16 v[84:87], v[148:151], v[180:183], v[84:87]
	v_mfma_f32_16x16x32_bf16 v[80:83], v[156:159], v[180:183], v[80:83]
	v_mfma_f32_16x16x32_bf16 v[68:71], v[148:151], v[188:191], v[68:71]
	v_mfma_f32_16x16x32_bf16 v[64:67], v[156:159], v[188:191], v[64:67]
	s_setprio 0
	s_barrier
	s_add_i32 s12, s65, s25
	v_lshl_add_u64 v[228:229], s[16:17], 0, v[196:197]
	s_mov_b32 m0, s12
	ds_read_b128 v[160:163], v225 offset:16384
	ds_read_b128 v[164:167], v225 offset:17408
	ds_read_b128 v[168:171], v225 offset:18432
	ds_read_b128 v[172:175], v225 offset:19456
	ds_read_b128 v[176:179], v225 offset:20480
	ds_read_b128 v[180:183], v225 offset:21504
	ds_read_b128 v[184:187], v225 offset:22528
	ds_read_b128 v[188:191], v225 offset:23552
	global_load_lds_dwordx4 v[228:229], off
	s_add_i32 m0, s12, 0x2000
	s_add_u32 s12, s16, 0xa0000
	v_lshl_add_u64 v[230:231], s[16:17], 0, v[200:201]
	s_addc_u32 s13, s17, 0
	s_add_i32 s65, s66, s25
	global_load_lds_dwordx4 v[230:231], off
	v_lshl_add_u64 v[232:233], s[12:13], 0, v[196:197]
	s_mov_b32 m0, s65
	v_lshl_add_u64 v[234:235], s[18:19], 0, v[198:199]
	global_load_lds_dwordx4 v[232:233], off
	v_lshl_add_u64 v[232:233], s[12:13], 0, v[200:201]
	s_add_i32 m0, s65, 0x2000
	s_nop 0
	global_load_lds_dwordx4 v[232:233], off
	v_lshl_add_u64 v[232:233], s[18:19], 0, v[194:195]
	s_mov_b32 m0, s26
	s_nop 0
	global_load_lds_dwordx4 v[232:233], off
	s_mov_b32 m0, s27
	s_nop 0
	global_load_lds_dwordx4 v[234:235], off
	s_waitcnt vmcnt(8)
	s_waitcnt lgkmcnt(0)
	s_barrier
	s_setprio 1
	v_mfma_f32_16x16x32_bf16 v[60:63], v[128:131], v[160:163], v[60:63]
	v_mfma_f32_16x16x32_bf16 v[56:59], v[136:139], v[160:163], v[56:59]
	v_mfma_f32_16x16x32_bf16 v[44:47], v[128:131], v[168:171], v[44:47]
	v_mfma_f32_16x16x32_bf16 v[40:43], v[136:139], v[168:171], v[40:43]
	v_mfma_f32_16x16x32_bf16 v[28:31], v[128:131], v[176:179], v[28:31]
	v_mfma_f32_16x16x32_bf16 v[24:27], v[136:139], v[176:179], v[24:27]
	v_mfma_f32_16x16x32_bf16 v[12:15], v[128:131], v[184:187], v[12:15]
	v_mfma_f32_16x16x32_bf16 v[8:11], v[136:139], v[184:187], v[8:11]
	v_mfma_f32_16x16x32_bf16 v[60:63], v[132:135], v[164:167], v[60:63]
	v_mfma_f32_16x16x32_bf16 v[56:59], v[140:143], v[164:167], v[56:59]
	v_mfma_f32_16x16x32_bf16 v[44:47], v[132:135], v[172:175], v[44:47]
	v_mfma_f32_16x16x32_bf16 v[40:43], v[140:143], v[172:175], v[40:43]
	v_mfma_f32_16x16x32_bf16 v[28:31], v[132:135], v[180:183], v[28:31]
	v_mfma_f32_16x16x32_bf16 v[24:27], v[140:143], v[180:183], v[24:27]
	v_mfma_f32_16x16x32_bf16 v[12:15], v[132:135], v[188:191], v[12:15]
	v_mfma_f32_16x16x32_bf16 v[8:11], v[140:143], v[188:191], v[8:11]
	v_mfma_f32_16x16x32_bf16 v[52:55], v[144:147], v[160:163], v[52:55]
	v_mfma_f32_16x16x32_bf16 v[48:51], v[152:155], v[160:163], v[48:51]
	v_mfma_f32_16x16x32_bf16 v[36:39], v[144:147], v[168:171], v[36:39]
	v_mfma_f32_16x16x32_bf16 v[32:35], v[152:155], v[168:171], v[32:35]
	v_mfma_f32_16x16x32_bf16 v[20:23], v[144:147], v[176:179], v[20:23]
	v_mfma_f32_16x16x32_bf16 v[16:19], v[152:155], v[176:179], v[16:19]
	v_mfma_f32_16x16x32_bf16 v[4:7], v[144:147], v[184:187], v[4:7]
	v_mfma_f32_16x16x32_bf16 v[0:3], v[152:155], v[184:187], v[0:3]
	v_mfma_f32_16x16x32_bf16 v[52:55], v[148:151], v[164:167], v[52:55]
	v_mfma_f32_16x16x32_bf16 v[48:51], v[156:159], v[164:167], v[48:51]
	v_mfma_f32_16x16x32_bf16 v[36:39], v[148:151], v[172:175], v[36:39]
	v_mfma_f32_16x16x32_bf16 v[32:35], v[156:159], v[172:175], v[32:35]
	v_mfma_f32_16x16x32_bf16 v[20:23], v[148:151], v[180:183], v[20:23]
	v_mfma_f32_16x16x32_bf16 v[16:19], v[156:159], v[180:183], v[16:19]
	v_mfma_f32_16x16x32_bf16 v[4:7], v[148:151], v[188:191], v[4:7]
	v_mfma_f32_16x16x32_bf16 v[0:3], v[156:159], v[188:191], v[0:3]
	s_setprio 0
	s_barrier
	s_add_i32 s65, 0, 0x18000
	s_add_i32 s66, 0, 0x1c000
	v_add_u32_e32 v140, s65, v222
	v_add_u32_e32 v156, s66, v222
	ds_read_b128 v[128:131], v140
	ds_read_b128 v[132:135], v140 offset:1024
	ds_read_b128 v[136:139], v140 offset:2048
	ds_read_b128 v[140:143], v140 offset:3072
	ds_read_b128 v[144:147], v156
	ds_read_b128 v[148:151], v156 offset:1024
	ds_read_b128 v[152:155], v156 offset:2048
	ds_read_b128 v[156:159], v156 offset:3072
	s_add_u32 s12, s18, 0xa0000
	s_addc_u32 s13, s19, 0
	s_mov_b32 m0, s28
	v_lshl_add_u64 v[236:237], s[12:13], 0, v[194:195]
	ds_read_b128 v[160:163], v225 offset:32768
	ds_read_b128 v[164:167], v225 offset:33792
	ds_read_b128 v[168:171], v225 offset:34816
	ds_read_b128 v[172:175], v225 offset:35840
	ds_read_b128 v[176:179], v225 offset:36864
	ds_read_b128 v[180:183], v225 offset:37888
	ds_read_b128 v[184:187], v225 offset:38912
	ds_read_b128 v[188:191], v225 offset:39936
	global_load_lds_dwordx4 v[236:237], off
	v_lshl_add_u64 v[236:237], s[12:13], 0, v[198:199]
	s_mov_b32 m0, s29
	s_nop 0
	global_load_lds_dwordx4 v[236:237], off
	s_waitcnt vmcnt(8)
	s_waitcnt lgkmcnt(0)
	s_barrier
	s_setprio 1
	v_mfma_f32_16x16x32_bf16 v[124:127], v[128:131], v[160:163], v[124:127]
	v_mfma_f32_16x16x32_bf16 v[120:123], v[136:139], v[160:163], v[120:123]
	v_mfma_f32_16x16x32_bf16 v[108:111], v[128:131], v[168:171], v[108:111]
	v_mfma_f32_16x16x32_bf16 v[104:107], v[136:139], v[168:171], v[104:107]
	v_mfma_f32_16x16x32_bf16 v[92:95], v[128:131], v[176:179], v[92:95]
	v_mfma_f32_16x16x32_bf16 v[88:91], v[136:139], v[176:179], v[88:91]
	v_mfma_f32_16x16x32_bf16 v[76:79], v[128:131], v[184:187], v[76:79]
	v_mfma_f32_16x16x32_bf16 v[72:75], v[136:139], v[184:187], v[72:75]
	v_mfma_f32_16x16x32_bf16 v[124:127], v[132:135], v[164:167], v[124:127]
	v_mfma_f32_16x16x32_bf16 v[120:123], v[140:143], v[164:167], v[120:123]
	v_mfma_f32_16x16x32_bf16 v[108:111], v[132:135], v[172:175], v[108:111]
	v_mfma_f32_16x16x32_bf16 v[104:107], v[140:143], v[172:175], v[104:107]
	v_mfma_f32_16x16x32_bf16 v[92:95], v[132:135], v[180:183], v[92:95]
	v_mfma_f32_16x16x32_bf16 v[88:91], v[140:143], v[180:183], v[88:91]
	v_mfma_f32_16x16x32_bf16 v[76:79], v[132:135], v[188:191], v[76:79]
	v_mfma_f32_16x16x32_bf16 v[72:75], v[140:143], v[188:191], v[72:75]
	v_mfma_f32_16x16x32_bf16 v[116:119], v[144:147], v[160:163], v[116:119]
	v_mfma_f32_16x16x32_bf16 v[112:115], v[152:155], v[160:163], v[112:115]
	v_mfma_f32_16x16x32_bf16 v[100:103], v[144:147], v[168:171], v[100:103]
	v_mfma_f32_16x16x32_bf16 v[96:99], v[152:155], v[168:171], v[96:99]
	v_mfma_f32_16x16x32_bf16 v[84:87], v[144:147], v[176:179], v[84:87]
	v_mfma_f32_16x16x32_bf16 v[80:83], v[152:155], v[176:179], v[80:83]
	v_mfma_f32_16x16x32_bf16 v[68:71], v[144:147], v[184:187], v[68:71]
	v_mfma_f32_16x16x32_bf16 v[64:67], v[152:155], v[184:187], v[64:67]
	v_mfma_f32_16x16x32_bf16 v[116:119], v[148:151], v[164:167], v[116:119]
	v_mfma_f32_16x16x32_bf16 v[112:115], v[156:159], v[164:167], v[112:115]
	v_mfma_f32_16x16x32_bf16 v[100:103], v[148:151], v[172:175], v[100:103]
	v_mfma_f32_16x16x32_bf16 v[96:99], v[156:159], v[172:175], v[96:99]
	v_mfma_f32_16x16x32_bf16 v[84:87], v[148:151], v[180:183], v[84:87]
	v_mfma_f32_16x16x32_bf16 v[80:83], v[156:159], v[180:183], v[80:83]
	v_mfma_f32_16x16x32_bf16 v[68:71], v[148:151], v[188:191], v[68:71]
	v_mfma_f32_16x16x32_bf16 v[64:67], v[156:159], v[188:191], v[64:67]
	s_setprio 0
	s_barrier
	s_add_i32 s12, s65, s25
	v_lshl_add_u64 v[228:229], v[228:229], 0, s[76:77]
	s_mov_b32 m0, s12
	ds_read_b128 v[160:163], v225 offset:49152
	ds_read_b128 v[164:167], v225 offset:50176
	ds_read_b128 v[168:171], v225 offset:51200
	ds_read_b128 v[172:175], v225 offset:52224
	ds_read_b128 v[176:179], v225 offset:53248
	ds_read_b128 v[180:183], v225 offset:54272
	ds_read_b128 v[184:187], v225 offset:55296
	ds_read_b128 v[188:191], v225 offset:56320
	global_load_lds_dwordx4 v[228:229], off
	s_add_i32 m0, s12, 0x2000
	s_add_u32 s12, s16, 0xa0080
	v_lshl_add_u64 v[228:229], v[230:231], 0, s[76:77]
	s_addc_u32 s13, s17, 0
	s_add_i32 s16, s66, s25
	global_load_lds_dwordx4 v[228:229], off
	v_lshl_add_u64 v[228:229], s[12:13], 0, v[196:197]
	s_mov_b32 m0, s16
	s_nop 0
	global_load_lds_dwordx4 v[228:229], off
	v_lshl_add_u64 v[228:229], s[12:13], 0, v[200:201]
	s_add_i32 m0, s16, 0x2000
	s_nop 0
	global_load_lds_dwordx4 v[228:229], off
	v_lshl_add_u64 v[228:229], v[232:233], 0, s[76:77]
	s_mov_b32 m0, s36
	s_nop 0
	global_load_lds_dwordx4 v[228:229], off
	v_lshl_add_u64 v[228:229], v[234:235], 0, s[76:77]
	s_mov_b32 m0, s37
	s_nop 0
	global_load_lds_dwordx4 v[228:229], off
	s_waitcnt vmcnt(8)
	s_waitcnt lgkmcnt(0)
	s_barrier
	s_setprio 1
	v_mfma_f32_16x16x32_bf16 v[60:63], v[128:131], v[160:163], v[60:63]
	v_mfma_f32_16x16x32_bf16 v[56:59], v[136:139], v[160:163], v[56:59]
	v_mfma_f32_16x16x32_bf16 v[44:47], v[128:131], v[168:171], v[44:47]
	v_mfma_f32_16x16x32_bf16 v[40:43], v[136:139], v[168:171], v[40:43]
	v_mfma_f32_16x16x32_bf16 v[28:31], v[128:131], v[176:179], v[28:31]
	v_mfma_f32_16x16x32_bf16 v[24:27], v[136:139], v[176:179], v[24:27]
	v_mfma_f32_16x16x32_bf16 v[12:15], v[128:131], v[184:187], v[12:15]
	v_mfma_f32_16x16x32_bf16 v[8:11], v[136:139], v[184:187], v[8:11]
	v_mfma_f32_16x16x32_bf16 v[60:63], v[132:135], v[164:167], v[60:63]
	v_mfma_f32_16x16x32_bf16 v[56:59], v[140:143], v[164:167], v[56:59]
	v_mfma_f32_16x16x32_bf16 v[44:47], v[132:135], v[172:175], v[44:47]
	v_mfma_f32_16x16x32_bf16 v[40:43], v[140:143], v[172:175], v[40:43]
	v_mfma_f32_16x16x32_bf16 v[28:31], v[132:135], v[180:183], v[28:31]
	v_mfma_f32_16x16x32_bf16 v[24:27], v[140:143], v[180:183], v[24:27]
	v_mfma_f32_16x16x32_bf16 v[12:15], v[132:135], v[188:191], v[12:15]
	v_mfma_f32_16x16x32_bf16 v[8:11], v[140:143], v[188:191], v[8:11]
	v_mfma_f32_16x16x32_bf16 v[52:55], v[144:147], v[160:163], v[52:55]
	v_mfma_f32_16x16x32_bf16 v[48:51], v[152:155], v[160:163], v[48:51]
	v_mfma_f32_16x16x32_bf16 v[36:39], v[144:147], v[168:171], v[36:39]
	v_mfma_f32_16x16x32_bf16 v[32:35], v[152:155], v[168:171], v[32:35]
	v_mfma_f32_16x16x32_bf16 v[20:23], v[144:147], v[176:179], v[20:23]
	v_mfma_f32_16x16x32_bf16 v[16:19], v[152:155], v[176:179], v[16:19]
	v_mfma_f32_16x16x32_bf16 v[4:7], v[144:147], v[184:187], v[4:7]
	v_mfma_f32_16x16x32_bf16 v[0:3], v[152:155], v[184:187], v[0:3]
	v_mfma_f32_16x16x32_bf16 v[52:55], v[148:151], v[164:167], v[52:55]
	v_mfma_f32_16x16x32_bf16 v[48:51], v[156:159], v[164:167], v[48:51]
	v_mfma_f32_16x16x32_bf16 v[36:39], v[148:151], v[172:175], v[36:39]
	v_mfma_f32_16x16x32_bf16 v[32:35], v[156:159], v[172:175], v[32:35]
	s_add_u32 s60, s60, 0x100
	s_addc_u32 s61, s61, 0
	s_add_i32 s62, s62, 1
	v_mfma_f32_16x16x32_bf16 v[20:23], v[148:151], v[180:183], v[20:23]
	v_mfma_f32_16x16x32_bf16 v[16:19], v[156:159], v[180:183], v[16:19]
	v_mfma_f32_16x16x32_bf16 v[4:7], v[148:151], v[188:191], v[4:7]
	v_mfma_f32_16x16x32_bf16 v[0:3], v[156:159], v[188:191], v[0:3]
	s_setprio 0
	s_barrier
	s_cmp_gt_u32 s63, 37
	s_mov_b64 s[12:13], s[14:15]
	s_mov_b32 s63, s64
	s_cbranch_scc1 .LBB0_1032

.LBB0_1099:
	s_add_u32 s18, s16, 0xfffc0080
	s_addc_u32 s19, s17, -1
	s_add_i32 s46, 0, 0x10000
	s_cmp_eq_u32 s45, 12
	s_cselect_b32 s21, s5, s19
	s_cselect_b32 s20, s9, s18
	s_cselect_b32 s19, s11, s44
	s_cselect_b32 s18, s42, s43
	s_add_i32 s48, 0, 0x14000
	v_add_u32_e32 v154, s46, v140
	v_add_u32_e32 v170, s48, v140
	ds_read_b128 v[142:145], v154
	ds_read_b128 v[146:149], v154 offset:1024
	ds_read_b128 v[150:153], v154 offset:2048
	ds_read_b128 v[154:157], v154 offset:3072
	ds_read_b128 v[158:161], v170
	ds_read_b128 v[162:165], v170 offset:1024
	ds_read_b128 v[166:169], v170 offset:2048
	ds_read_b128 v[170:173], v170 offset:3072
	v_lshl_add_u64 v[190:191], s[16:17], 0, v[136:137]
	s_add_i32 m0, s28, 0xc000
	ds_read_b128 v[174:177], v141
	ds_read_b128 v[178:181], v141 offset:1024
	ds_read_b128 v[182:185], v141 offset:2048
	ds_read_b128 v[186:189], v141 offset:3072
	ds_read_b128 v[194:197], v141 offset:4096
	ds_read_b128 v[198:201], v141 offset:5120
	ds_read_b128 v[202:205], v141 offset:6144
	ds_read_b128 v[220:223], v141 offset:7168
	global_load_lds_dwordx4 v[190:191], off
	v_lshl_add_u64 v[190:191], s[16:17], 0, v[134:135]
	s_add_i32 m0, s28, 0xe000
	s_nop 0
	global_load_lds_dwordx4 v[190:191], off
	s_waitcnt vmcnt(8)
	s_waitcnt lgkmcnt(0)
	s_barrier
	s_setprio 1
	v_mfma_f32_16x16x32_bf16 v[124:127], v[142:145], v[174:177], v[124:127]
	v_mfma_f32_16x16x32_bf16 v[120:123], v[150:153], v[174:177], v[120:123]
	v_mfma_f32_16x16x32_bf16 v[116:119], v[142:145], v[182:185], v[116:119]
	v_mfma_f32_16x16x32_bf16 v[112:115], v[150:153], v[182:185], v[112:115]
	v_mfma_f32_16x16x32_bf16 v[100:103], v[142:145], v[194:197], v[100:103]
	v_mfma_f32_16x16x32_bf16 v[96:99], v[150:153], v[194:197], v[96:99]
	v_mfma_f32_16x16x32_bf16 v[84:87], v[142:145], v[202:205], v[84:87]
	v_mfma_f32_16x16x32_bf16 v[80:83], v[150:153], v[202:205], v[80:83]
	v_mfma_f32_16x16x32_bf16 v[124:127], v[146:149], v[178:181], v[124:127]
	v_mfma_f32_16x16x32_bf16 v[120:123], v[154:157], v[178:181], v[120:123]
	v_mfma_f32_16x16x32_bf16 v[116:119], v[146:149], v[186:189], v[116:119]
	v_mfma_f32_16x16x32_bf16 v[112:115], v[154:157], v[186:189], v[112:115]
	v_mfma_f32_16x16x32_bf16 v[100:103], v[146:149], v[198:201], v[100:103]
	v_mfma_f32_16x16x32_bf16 v[96:99], v[154:157], v[198:201], v[96:99]
	v_mfma_f32_16x16x32_bf16 v[84:87], v[146:149], v[220:223], v[84:87]
	v_mfma_f32_16x16x32_bf16 v[80:83], v[154:157], v[220:223], v[80:83]
	v_mfma_f32_16x16x32_bf16 v[108:111], v[158:161], v[174:177], v[108:111]
	v_mfma_f32_16x16x32_bf16 v[104:107], v[166:169], v[174:177], v[104:107]
	v_mfma_f32_16x16x32_bf16 v[92:95], v[158:161], v[182:185], v[92:95]
	v_mfma_f32_16x16x32_bf16 v[88:91], v[166:169], v[182:185], v[88:91]
	v_mfma_f32_16x16x32_bf16 v[76:79], v[158:161], v[194:197], v[76:79]
	v_mfma_f32_16x16x32_bf16 v[72:75], v[166:169], v[194:197], v[72:75]
	v_mfma_f32_16x16x32_bf16 v[68:71], v[158:161], v[202:205], v[68:71]
	v_mfma_f32_16x16x32_bf16 v[64:67], v[166:169], v[202:205], v[64:67]
	v_mfma_f32_16x16x32_bf16 v[108:111], v[162:165], v[178:181], v[108:111]
	v_mfma_f32_16x16x32_bf16 v[104:107], v[170:173], v[178:181], v[104:107]
	v_mfma_f32_16x16x32_bf16 v[92:95], v[162:165], v[186:189], v[92:95]
	v_mfma_f32_16x16x32_bf16 v[88:91], v[170:173], v[186:189], v[88:91]
	v_mfma_f32_16x16x32_bf16 v[76:79], v[162:165], v[198:201], v[76:79]
	v_mfma_f32_16x16x32_bf16 v[72:75], v[170:173], v[198:201], v[72:75]
	v_mfma_f32_16x16x32_bf16 v[68:71], v[162:165], v[220:223], v[68:71]
	v_mfma_f32_16x16x32_bf16 v[64:67], v[170:173], v[220:223], v[64:67]
	s_setprio 0
	s_barrier
	s_add_i32 s46, s46, s27
	v_lshl_add_u64 v[190:191], s[18:19], 0, v[192:193]
	s_mov_b32 m0, s46
	ds_read_b128 v[174:177], v141 offset:16384
	ds_read_b128 v[178:181], v141 offset:17408
	ds_read_b128 v[182:185], v141 offset:18432
	ds_read_b128 v[186:189], v141 offset:19456
	ds_read_b128 v[194:197], v141 offset:20480
	ds_read_b128 v[198:201], v141 offset:21504
	ds_read_b128 v[202:205], v141 offset:22528
	ds_read_b128 v[220:223], v141 offset:23552
	global_load_lds_dwordx4 v[190:191], off
	s_add_i32 m0, s46, 0x2000
	s_add_u32 s46, s18, 0x40000
	v_lshl_add_u64 v[224:225], s[18:19], 0, v[132:133]
	s_addc_u32 s47, s19, 0
	s_add_i32 s48, s48, s27
	global_load_lds_dwordx4 v[224:225], off
	v_lshl_add_u64 v[226:227], s[46:47], 0, v[192:193]
	s_mov_b32 m0, s48
	v_lshl_add_u64 v[228:229], s[20:21], 0, v[130:131]
	global_load_lds_dwordx4 v[226:227], off
	v_lshl_add_u64 v[226:227], s[46:47], 0, v[132:133]
	s_add_i32 m0, s48, 0x2000
	s_nop 0
	global_load_lds_dwordx4 v[226:227], off
	v_lshl_add_u64 v[226:227], s[20:21], 0, v[128:129]
	s_mov_b32 m0, s28
	s_nop 0
	global_load_lds_dwordx4 v[226:227], off
	s_mov_b32 m0, s29
	s_nop 0
	global_load_lds_dwordx4 v[228:229], off
	s_waitcnt vmcnt(8)
	s_waitcnt lgkmcnt(0)
	s_barrier
	s_setprio 1
	v_mfma_f32_16x16x32_bf16 v[60:63], v[142:145], v[174:177], v[60:63]
	v_mfma_f32_16x16x32_bf16 v[56:59], v[150:153], v[174:177], v[56:59]
	v_mfma_f32_16x16x32_bf16 v[52:55], v[142:145], v[182:185], v[52:55]
	v_mfma_f32_16x16x32_bf16 v[48:51], v[150:153], v[182:185], v[48:51]
	v_mfma_f32_16x16x32_bf16 v[36:39], v[142:145], v[194:197], v[36:39]
	v_mfma_f32_16x16x32_bf16 v[32:35], v[150:153], v[194:197], v[32:35]
	v_mfma_f32_16x16x32_bf16 v[20:23], v[142:145], v[202:205], v[20:23]
	v_mfma_f32_16x16x32_bf16 v[16:19], v[150:153], v[202:205], v[16:19]
	v_mfma_f32_16x16x32_bf16 v[60:63], v[146:149], v[178:181], v[60:63]
	v_mfma_f32_16x16x32_bf16 v[56:59], v[154:157], v[178:181], v[56:59]
	v_mfma_f32_16x16x32_bf16 v[52:55], v[146:149], v[186:189], v[52:55]
	v_mfma_f32_16x16x32_bf16 v[48:51], v[154:157], v[186:189], v[48:51]
	v_mfma_f32_16x16x32_bf16 v[36:39], v[146:149], v[198:201], v[36:39]
	v_mfma_f32_16x16x32_bf16 v[32:35], v[154:157], v[198:201], v[32:35]
	v_mfma_f32_16x16x32_bf16 v[20:23], v[146:149], v[220:223], v[20:23]
	v_mfma_f32_16x16x32_bf16 v[16:19], v[154:157], v[220:223], v[16:19]
	v_mfma_f32_16x16x32_bf16 v[44:47], v[158:161], v[174:177], v[44:47]
	v_mfma_f32_16x16x32_bf16 v[40:43], v[166:169], v[174:177], v[40:43]
	v_mfma_f32_16x16x32_bf16 v[28:31], v[158:161], v[182:185], v[28:31]
	v_mfma_f32_16x16x32_bf16 v[24:27], v[166:169], v[182:185], v[24:27]
	v_mfma_f32_16x16x32_bf16 v[12:15], v[158:161], v[194:197], v[12:15]
	v_mfma_f32_16x16x32_bf16 v[8:11], v[166:169], v[194:197], v[8:11]
	v_mfma_f32_16x16x32_bf16 v[4:7], v[158:161], v[202:205], v[4:7]
	v_mfma_f32_16x16x32_bf16 v[0:3], v[166:169], v[202:205], v[0:3]
	v_mfma_f32_16x16x32_bf16 v[44:47], v[162:165], v[178:181], v[44:47]
	v_mfma_f32_16x16x32_bf16 v[40:43], v[170:173], v[178:181], v[40:43]
	v_mfma_f32_16x16x32_bf16 v[28:31], v[162:165], v[186:189], v[28:31]
	v_mfma_f32_16x16x32_bf16 v[24:27], v[170:173], v[186:189], v[24:27]
	v_mfma_f32_16x16x32_bf16 v[12:15], v[162:165], v[198:201], v[12:15]
	v_mfma_f32_16x16x32_bf16 v[8:11], v[170:173], v[198:201], v[8:11]
	v_mfma_f32_16x16x32_bf16 v[4:7], v[162:165], v[220:223], v[4:7]
	v_mfma_f32_16x16x32_bf16 v[0:3], v[170:173], v[220:223], v[0:3]
	s_setprio 0
	s_barrier
	s_add_i32 s46, 0, 0x18000
	s_add_i32 s47, 0, 0x1c000
	v_add_u32_e32 v154, s46, v140
	v_add_u32_e32 v170, s47, v140
	ds_read_b128 v[142:145], v154
	ds_read_b128 v[146:149], v154 offset:1024
	ds_read_b128 v[150:153], v154 offset:2048
	ds_read_b128 v[154:157], v154 offset:3072
	ds_read_b128 v[158:161], v170
	ds_read_b128 v[162:165], v170 offset:1024
	ds_read_b128 v[166:169], v170 offset:2048
	ds_read_b128 v[170:173], v170 offset:3072
	s_add_u32 s20, s20, 0x40000
	s_addc_u32 s21, s21, 0
	s_mov_b32 m0, s30
	v_lshl_add_u64 v[230:231], s[20:21], 0, v[128:129]
	ds_read_b128 v[174:177], v141 offset:32768
	ds_read_b128 v[178:181], v141 offset:33792
	ds_read_b128 v[182:185], v141 offset:34816
	ds_read_b128 v[186:189], v141 offset:35840
	ds_read_b128 v[194:197], v141 offset:36864
	ds_read_b128 v[198:201], v141 offset:37888
	ds_read_b128 v[202:205], v141 offset:38912
	ds_read_b128 v[220:223], v141 offset:39936
	global_load_lds_dwordx4 v[230:231], off
	v_lshl_add_u64 v[230:231], s[20:21], 0, v[130:131]
	s_mov_b32 m0, s31
	s_nop 0
	global_load_lds_dwordx4 v[230:231], off
	s_waitcnt vmcnt(8)
	s_waitcnt lgkmcnt(0)
	s_barrier
	s_setprio 1
	v_mfma_f32_16x16x32_bf16 v[124:127], v[142:145], v[174:177], v[124:127]
	v_mfma_f32_16x16x32_bf16 v[120:123], v[150:153], v[174:177], v[120:123]
	v_mfma_f32_16x16x32_bf16 v[116:119], v[142:145], v[182:185], v[116:119]
	v_mfma_f32_16x16x32_bf16 v[112:115], v[150:153], v[182:185], v[112:115]
	v_mfma_f32_16x16x32_bf16 v[100:103], v[142:145], v[194:197], v[100:103]
	v_mfma_f32_16x16x32_bf16 v[96:99], v[150:153], v[194:197], v[96:99]
	v_mfma_f32_16x16x32_bf16 v[84:87], v[142:145], v[202:205], v[84:87]
	v_mfma_f32_16x16x32_bf16 v[80:83], v[150:153], v[202:205], v[80:83]
	v_mfma_f32_16x16x32_bf16 v[124:127], v[146:149], v[178:181], v[124:127]
	v_mfma_f32_16x16x32_bf16 v[120:123], v[154:157], v[178:181], v[120:123]
	v_mfma_f32_16x16x32_bf16 v[116:119], v[146:149], v[186:189], v[116:119]
	v_mfma_f32_16x16x32_bf16 v[112:115], v[154:157], v[186:189], v[112:115]
	v_mfma_f32_16x16x32_bf16 v[100:103], v[146:149], v[198:201], v[100:103]
	v_mfma_f32_16x16x32_bf16 v[96:99], v[154:157], v[198:201], v[96:99]
	v_mfma_f32_16x16x32_bf16 v[84:87], v[146:149], v[220:223], v[84:87]
	v_mfma_f32_16x16x32_bf16 v[80:83], v[154:157], v[220:223], v[80:83]
	v_mfma_f32_16x16x32_bf16 v[108:111], v[158:161], v[174:177], v[108:111]
	v_mfma_f32_16x16x32_bf16 v[104:107], v[166:169], v[174:177], v[104:107]
	v_mfma_f32_16x16x32_bf16 v[92:95], v[158:161], v[182:185], v[92:95]
	v_mfma_f32_16x16x32_bf16 v[88:91], v[166:169], v[182:185], v[88:91]
	v_mfma_f32_16x16x32_bf16 v[76:79], v[158:161], v[194:197], v[76:79]
	v_mfma_f32_16x16x32_bf16 v[72:75], v[166:169], v[194:197], v[72:75]
	v_mfma_f32_16x16x32_bf16 v[68:71], v[158:161], v[202:205], v[68:71]
	v_mfma_f32_16x16x32_bf16 v[64:67], v[166:169], v[202:205], v[64:67]
	v_mfma_f32_16x16x32_bf16 v[108:111], v[162:165], v[178:181], v[108:111]
	v_mfma_f32_16x16x32_bf16 v[104:107], v[170:173], v[178:181], v[104:107]
	v_mfma_f32_16x16x32_bf16 v[92:95], v[162:165], v[186:189], v[92:95]
	v_mfma_f32_16x16x32_bf16 v[88:91], v[170:173], v[186:189], v[88:91]
	v_mfma_f32_16x16x32_bf16 v[76:79], v[162:165], v[198:201], v[76:79]
	v_mfma_f32_16x16x32_bf16 v[72:75], v[170:173], v[198:201], v[72:75]
	v_mfma_f32_16x16x32_bf16 v[68:71], v[162:165], v[220:223], v[68:71]
	v_mfma_f32_16x16x32_bf16 v[64:67], v[170:173], v[220:223], v[64:67]
	s_setprio 0
	s_barrier
	s_add_i32 s20, s46, s27
	v_lshl_add_u64 v[190:191], v[190:191], 0, s[76:77]
	s_mov_b32 m0, s20
	ds_read_b128 v[174:177], v141 offset:49152
	ds_read_b128 v[178:181], v141 offset:50176
	ds_read_b128 v[182:185], v141 offset:51200
	ds_read_b128 v[186:189], v141 offset:52224
	ds_read_b128 v[194:197], v141 offset:53248
	ds_read_b128 v[198:201], v141 offset:54272
	ds_read_b128 v[202:205], v141 offset:55296
	ds_read_b128 v[220:223], v141 offset:56320
	global_load_lds_dwordx4 v[190:191], off
	s_add_i32 m0, s20, 0x2000
	s_add_u32 s18, s18, 0x40080
	v_lshl_add_u64 v[190:191], v[224:225], 0, s[76:77]
	s_addc_u32 s19, s19, 0
	s_add_i32 s20, s47, s27
	global_load_lds_dwordx4 v[190:191], off
	v_lshl_add_u64 v[190:191], s[18:19], 0, v[192:193]
	s_mov_b32 m0, s20
	s_nop 0
	global_load_lds_dwordx4 v[190:191], off
	v_lshl_add_u64 v[190:191], s[18:19], 0, v[132:133]
	s_add_i32 m0, s20, 0x2000
	s_nop 0
	global_load_lds_dwordx4 v[190:191], off
	v_lshl_add_u64 v[190:191], v[226:227], 0, s[76:77]
	s_mov_b32 m0, s36
	s_nop 0
	global_load_lds_dwordx4 v[190:191], off
	v_lshl_add_u64 v[190:191], v[228:229], 0, s[76:77]
	s_mov_b32 m0, s37
	s_nop 0
	global_load_lds_dwordx4 v[190:191], off
	s_waitcnt vmcnt(8)
	s_waitcnt lgkmcnt(0)
	s_barrier
	s_setprio 1
	v_mfma_f32_16x16x32_bf16 v[60:63], v[142:145], v[174:177], v[60:63]
	v_mfma_f32_16x16x32_bf16 v[56:59], v[150:153], v[174:177], v[56:59]
	v_mfma_f32_16x16x32_bf16 v[52:55], v[142:145], v[182:185], v[52:55]
	v_mfma_f32_16x16x32_bf16 v[48:51], v[150:153], v[182:185], v[48:51]
	v_mfma_f32_16x16x32_bf16 v[36:39], v[142:145], v[194:197], v[36:39]
	v_mfma_f32_16x16x32_bf16 v[32:35], v[150:153], v[194:197], v[32:35]
	v_mfma_f32_16x16x32_bf16 v[20:23], v[142:145], v[202:205], v[20:23]
	v_mfma_f32_16x16x32_bf16 v[16:19], v[150:153], v[202:205], v[16:19]
	v_mfma_f32_16x16x32_bf16 v[60:63], v[146:149], v[178:181], v[60:63]
	v_mfma_f32_16x16x32_bf16 v[56:59], v[154:157], v[178:181], v[56:59]
	v_mfma_f32_16x16x32_bf16 v[52:55], v[146:149], v[186:189], v[52:55]
	v_mfma_f32_16x16x32_bf16 v[48:51], v[154:157], v[186:189], v[48:51]
	v_mfma_f32_16x16x32_bf16 v[36:39], v[146:149], v[198:201], v[36:39]
	v_mfma_f32_16x16x32_bf16 v[32:35], v[154:157], v[198:201], v[32:35]
	v_mfma_f32_16x16x32_bf16 v[20:23], v[146:149], v[220:223], v[20:23]
	v_mfma_f32_16x16x32_bf16 v[16:19], v[154:157], v[220:223], v[16:19]
	v_mfma_f32_16x16x32_bf16 v[44:47], v[158:161], v[174:177], v[44:47]
	v_mfma_f32_16x16x32_bf16 v[40:43], v[166:169], v[174:177], v[40:43]
	v_mfma_f32_16x16x32_bf16 v[28:31], v[158:161], v[182:185], v[28:31]
	v_mfma_f32_16x16x32_bf16 v[24:27], v[166:169], v[182:185], v[24:27]
	v_mfma_f32_16x16x32_bf16 v[12:15], v[158:161], v[194:197], v[12:15]
	v_mfma_f32_16x16x32_bf16 v[8:11], v[166:169], v[194:197], v[8:11]
	v_mfma_f32_16x16x32_bf16 v[4:7], v[158:161], v[202:205], v[4:7]
	v_mfma_f32_16x16x32_bf16 v[0:3], v[166:169], v[202:205], v[0:3]
	v_mfma_f32_16x16x32_bf16 v[44:47], v[162:165], v[178:181], v[44:47]
	v_mfma_f32_16x16x32_bf16 v[40:43], v[170:173], v[178:181], v[40:43]
	v_mfma_f32_16x16x32_bf16 v[28:31], v[162:165], v[186:189], v[28:31]
	v_mfma_f32_16x16x32_bf16 v[24:27], v[170:173], v[186:189], v[24:27]
	s_add_i32 s45, s45, 2
	s_add_u32 s43, s43, 0x100
	s_addc_u32 s44, s44, 0
	s_add_u32 s16, s16, 0x100
	s_addc_u32 s17, s17, 0
	v_mfma_f32_16x16x32_bf16 v[12:15], v[162:165], v[198:201], v[12:15]
	v_mfma_f32_16x16x32_bf16 v[8:11], v[170:173], v[198:201], v[8:11]
	v_mfma_f32_16x16x32_bf16 v[4:7], v[162:165], v[220:223], v[4:7]
	v_mfma_f32_16x16x32_bf16 v[0:3], v[170:173], v[220:223], v[0:3]
	s_setprio 0
	s_barrier
	s_cmp_gt_u32 s45, 13
	s_cbranch_scc0 .LBB0_1099
	s_and_b64 vcc, exec, s[2:3]
	s_cbranch_vccz .LBB0_1102
	s_barrier
